# P2 conv outputs (q_dec, k_dec 16-byte row stores) issued as nt stores
# baseline (speedup 1.0000x reference)
.LBB0_350:
	s_andn2_b64 vcc, exec, s[4:5]
	s_cbranch_vccnz .LBB0_353
	s_cmp_lg_u32 s14, 1
	s_cbranch_scc1 .LBB0_353
	v_lshl_add_u32 v0, v17, 5, 0
	v_add_u32_e32 v179, 0x17b00, v0
	v_lshlrev_b32_e32 v0, 16, v84
	v_and_b32_e32 v1, 0xffff0000, v84
	v_mov_b32_e32 v20, v48
	v_mov_b32_e32 v21, v52
	v_lshlrev_b32_e32 v152, 16, v80
	v_and_b32_e32 v153, 0xffff0000, v80
	v_pk_fma_f32 v[0:1], v[20:21], v[0:1], 0 op_sel_hi:[1,1,0]
	v_mov_b32_e32 v22, v49
	v_mov_b32_e32 v23, v53
	v_lshlrev_b32_e32 v2, 16, v85
	v_and_b32_e32 v3, 0xffff0000, v85
	v_mov_b32_e32 v28, v56
	v_mov_b32_e32 v29, v60
	v_lshlrev_b32_e32 v162, 16, v88
	v_and_b32_e32 v163, 0xffff0000, v88
	v_pk_fma_f32 v[0:1], v[22:23], v[152:153], v[0:1]
	v_mov_b32_e32 v24, v50
	v_mov_b32_e32 v25, v54
	v_lshlrev_b32_e32 v164, 16, v81
	v_and_b32_e32 v165, 0xffff0000, v81
	v_pk_fma_f32 v[2:3], v[28:29], v[2:3], 0 op_sel_hi:[1,1,0]
	v_mov_b32_e32 v30, v57
	v_mov_b32_e32 v31, v61
	v_lshlrev_b32_e32 v19, 3, v17
	v_lshlrev_b32_e32 v144, 16, v92
	v_and_b32_e32 v145, 0xffff0000, v92
	v_pk_fma_f32 v[0:1], v[24:25], v[162:163], v[0:1]
	v_mov_b32_e32 v26, v51
	v_mov_b32_e32 v27, v55
	v_lshlrev_b32_e32 v166, 16, v89
	v_and_b32_e32 v167, 0xffff0000, v89
	v_pk_fma_f32 v[2:3], v[30:31], v[164:165], v[2:3]
	v_mov_b32_e32 v32, v58
	v_mov_b32_e32 v33, v62
	v_lshlrev_b32_e32 v4, 16, v86
	v_and_b32_e32 v5, 0xffff0000, v86
	v_mov_b32_e32 v36, v64
	v_mov_b32_e32 v37, v68
	v_pk_fma_f32 v[0:1], v[26:27], v[144:145], v[0:1]
	v_lshlrev_b32_e32 v146, 16, v93
	v_and_b32_e32 v147, 0xffff0000, v93
	v_pk_fma_f32 v[2:3], v[32:33], v[166:167], v[2:3]
	v_mov_b32_e32 v34, v59
	v_mov_b32_e32 v35, v63
	v_lshlrev_b32_e32 v182, 16, v82
	v_and_b32_e32 v183, 0xffff0000, v82
	v_pk_fma_f32 v[4:5], v[36:37], v[4:5], 0 op_sel_hi:[1,1,0]
	v_mov_b32_e32 v38, v65
	v_mov_b32_e32 v39, v69
	v_cmp_gt_u32_e32 vcc, s3, v19
	v_pk_fma_f32 v[2:3], v[34:35], v[146:147], v[2:3]
	v_lshlrev_b32_e32 v168, 16, v90
	v_and_b32_e32 v169, 0xffff0000, v90
	v_pk_fma_f32 v[4:5], v[38:39], v[182:183], v[4:5]
	v_mov_b32_e32 v42, v66
	v_mov_b32_e32 v43, v70
	v_lshlrev_b32_e32 v6, 16, v87
	v_and_b32_e32 v7, 0xffff0000, v87
	v_mov_b32_e32 v46, v72
	v_mov_b32_e32 v47, v76
	v_cndmask_b32_e32 v1, 0, v1, vcc
	v_cndmask_b32_e32 v0, 0, v0, vcc
	v_lshlrev_b32_e32 v148, 16, v94
	v_and_b32_e32 v149, 0xffff0000, v94
	v_pk_fma_f32 v[4:5], v[42:43], v[168:169], v[4:5]
	v_mov_b32_e32 v44, v67
	v_mov_b32_e32 v45, v71
	v_lshlrev_b32_e32 v184, 16, v83
	v_and_b32_e32 v185, 0xffff0000, v83
	v_pk_fma_f32 v[6:7], v[46:47], v[6:7], 0 op_sel_hi:[1,1,0]
	v_mov_b32_e32 v134, v73
	v_mov_b32_e32 v135, v77
	v_cndmask_b32_e32 v3, 0, v3, vcc
	v_cndmask_b32_e32 v2, 0, v2, vcc
	v_mul_f32_e32 v8, 0xbfb8aa3b, v0
	v_mul_f32_e32 v9, 0xbfb8aa3b, v1
	v_pk_fma_f32 v[4:5], v[44:45], v[148:149], v[4:5]
	v_lshlrev_b32_e32 v170, 16, v91
	v_and_b32_e32 v171, 0xffff0000, v91
	v_pk_fma_f32 v[6:7], v[134:135], v[184:185], v[6:7]
	v_mov_b32_e32 v140, v74
	v_mov_b32_e32 v141, v78
	v_exp_f32_e32 v8, v8
	v_exp_f32_e32 v9, v9
	v_mul_f32_e32 v10, 0xbfb8aa3b, v2
	v_mul_f32_e32 v11, 0xbfb8aa3b, v3
	v_lshlrev_b32_e32 v150, 16, v95
	v_and_b32_e32 v151, 0xffff0000, v95
	v_pk_fma_f32 v[6:7], v[140:141], v[170:171], v[6:7]
	v_mov_b32_e32 v142, v75
	v_mov_b32_e32 v143, v79
	v_cndmask_b32_e32 v5, 0, v5, vcc
	v_cndmask_b32_e32 v4, 0, v4, vcc
	v_exp_f32_e32 v10, v10
	v_exp_f32_e32 v11, v11
	v_pk_fma_f32 v[6:7], v[142:143], v[150:151], v[6:7]
	v_mul_f32_e32 v12, 0xbfb8aa3b, v4
	v_mul_f32_e32 v13, 0xbfb8aa3b, v5
	v_cndmask_b32_e32 v7, 0, v7, vcc
	v_cndmask_b32_e32 v6, 0, v6, vcc
	v_exp_f32_e32 v12, v12
	v_exp_f32_e32 v13, v13
	v_add_f32_e32 v8, 1.0, v8
	v_add_f32_e32 v9, 1.0, v9
	v_mul_f32_e32 v14, 0xbfb8aa3b, v6
	v_mul_f32_e32 v15, 0xbfb8aa3b, v7
	v_rcp_f32_e32 v8, v8
	v_rcp_f32_e32 v9, v9
	v_add_f32_e32 v10, 1.0, v10
	v_add_f32_e32 v11, 1.0, v11
	v_exp_f32_e32 v14, v14
	v_exp_f32_e32 v15, v15
	v_rcp_f32_e32 v10, v10
	v_rcp_f32_e32 v11, v11
	v_add_f32_e32 v12, 1.0, v12
	v_add_f32_e32 v13, 1.0, v13
	v_rcp_f32_e32 v12, v12
	v_rcp_f32_e32 v13, v13
	v_add_f32_e32 v14, 1.0, v14
	v_add_f32_e32 v15, 1.0, v15
	v_pk_mul_f32 v[160:161], v[0:1], v[8:9]
	v_rcp_f32_e32 v14, v14
	v_rcp_f32_e32 v15, v15
	v_pk_mul_f32 v[158:159], v[2:3], v[10:11]
	v_pk_mul_f32 v[0:1], v[160:161], v[160:161]
	v_pk_mul_f32 v[2:3], v[158:159], v[158:159]
	v_add_f32_e32 v0, v0, v1
	v_pk_mul_f32 v[156:157], v[4:5], v[12:13]
	v_add_f32_e32 v0, v2, v0
	v_pk_mul_f32 v[4:5], v[156:157], v[156:157]
	v_add_f32_e32 v0, v3, v0
	v_pk_mul_f32 v[40:41], v[6:7], v[14:15]
	v_add_f32_e32 v0, v4, v0
	v_pk_mul_f32 v[6:7], v[40:41], v[40:41]
	v_add_f32_e32 v0, v5, v0
	v_add_f32_e32 v0, v6, v0
	v_add_f32_e32 v0, v7, v0
	v_pk_fma_f32 v[152:153], v[20:21], v[152:153], 0 op_sel_hi:[1,1,0]
	v_or_b32_e32 v198, 1, v19
	v_add_f32_dpp v0, v0, v0 quad_perm:[1,0,3,2] row_mask:0xf bank_mask:0xf bound_ctrl:1
	v_pk_fma_f32 v[152:153], v[22:23], v[162:163], v[152:153]
	v_cmp_gt_u32_e32 vcc, s3, v198
	v_add_f32_dpp v0, v0, v0 quad_perm:[2,3,0,1] row_mask:0xf bank_mask:0xf bound_ctrl:1
	v_pk_fma_f32 v[152:153], v[24:25], v[144:145], v[152:153]
	s_lshl_b64 s[4:5], s[40:41], 14
	v_add_f32_dpp v0, v0, v0 row_half_mirror row_mask:0xf bank_mask:0xf bound_ctrl:1
	s_add_u32 s4, s74, s4
	s_addc_u32 s5, s75, s5
	v_add_f32_dpp v0, v0, v0 row_mirror row_mask:0xf bank_mask:0xf bound_ctrl:1
	v_add_f32_e32 v0, 0x358637bd, v0
	v_rsq_f32_e32 v178, v0
	ds_read_b128 v[12:15], v179
	ds_read_b128 v[4:7], v179 offset:16
	ds_read_b128 v[8:11], v179 offset:256
	ds_read_b128 v[0:3], v179 offset:272
	v_pk_fma_f32 v[184:185], v[46:47], v[184:185], 0 op_sel_hi:[1,1,0]
	v_pk_mul_f32 v[160:161], v[160:161], v[178:179] op_sel_hi:[1,0]
	v_pk_mul_f32 v[180:181], v[158:159], v[178:179] op_sel_hi:[1,0]
	v_pk_mul_f32 v[186:187], v[156:157], v[178:179] op_sel_hi:[1,0]
	v_pk_mul_f32 v[188:189], v[40:41], v[178:179] op_sel_hi:[1,0]
	v_mul_u32_u24_e32 v41, 0x880, v17
	v_lshlrev_b32_e32 v40, 4, v177
	v_cvt_pk_bf16_f32 v156, v160, v161
	v_cvt_pk_bf16_f32 v157, v180, v181
	v_cvt_pk_bf16_f32 v158, v186, v187
	v_cvt_pk_bf16_f32 v159, v188, v189
	v_add3_u32 v41, 0, v41, v40
	ds_write_b128 v41, v[156:159] offset:17408
	s_waitcnt lgkmcnt(4)
	v_pk_mul_f32 v[156:157], v[12:13], v[160:161] op_sel_hi:[0,1]
	v_pk_mul_f32 v[158:159], v[12:13], v[180:181] op_sel_hi:[0,1]
	v_cvt_pk_bf16_f32 v156, v156, v157
	v_cvt_pk_bf16_f32 v157, v158, v159
	v_pk_mul_f32 v[158:159], v[12:13], v[186:187] op_sel_hi:[0,1]
	v_pk_mul_f32 v[178:179], v[12:13], v[188:189] op_sel_hi:[0,1]
	v_cvt_pk_bf16_f32 v158, v158, v159
	v_cvt_pk_bf16_f32 v159, v178, v179
	ds_write_b128 v41, v[156:159] offset:52224
	s_waitcnt lgkmcnt(3)
	v_pk_mul_f32 v[156:157], v[8:9], v[160:161] op_sel_hi:[0,1]
	v_cvt_pk_bf16_f32 v178, v156, v157
	v_pk_mul_f32 v[156:157], v[8:9], v[180:181] op_sel_hi:[0,1]
	v_cvt_pk_bf16_f32 v179, v156, v157
	v_pk_mul_f32 v[156:157], v[8:9], v[186:187] op_sel_hi:[0,1]
	v_lshlrev_b32_e32 v160, 16, v96
	v_and_b32_e32 v161, 0xffff0000, v96
	v_cvt_pk_bf16_f32 v180, v156, v157
	v_pk_mul_f32 v[156:157], v[8:9], v[188:189] op_sel_hi:[0,1]
	v_pk_fma_f32 v[188:189], v[26:27], v[160:161], v[152:153]
	v_pk_fma_f32 v[152:153], v[28:29], v[164:165], 0 op_sel_hi:[1,1,0]
	v_cndmask_b32_e32 v188, 0, v188, vcc
	v_cndmask_b32_e32 v189, 0, v189, vcc
	v_mul_f32_e32 v41, 0xbfb8aa3b, v188
	v_pk_fma_f32 v[152:153], v[30:31], v[166:167], v[152:153]
	v_exp_f32_e32 v41, v41
	v_mul_f32_e32 v190, 0xbfb8aa3b, v189
	v_lshlrev_b32_e32 v158, 16, v97
	v_and_b32_e32 v159, 0xffff0000, v97
	v_pk_fma_f32 v[152:153], v[32:33], v[146:147], v[152:153]
	v_exp_f32_e32 v191, v190
	v_pk_fma_f32 v[164:165], v[34:35], v[158:159], v[152:153]
	v_pk_fma_f32 v[152:153], v[36:37], v[182:183], 0 op_sel_hi:[1,1,0]
	v_cvt_pk_bf16_f32 v181, v156, v157
	v_lshlrev_b32_e32 v156, 11, v17
	v_mov_b32_e32 v157, v132
	v_pk_fma_f32 v[152:153], v[38:39], v[168:169], v[152:153]
	v_lshl_add_u64 v[186:187], s[4:5], 0, v[156:157]
	v_lshlrev_b32_e32 v156, 16, v98
	v_and_b32_e32 v157, 0xffff0000, v98
	v_pk_fma_f32 v[152:153], v[42:43], v[148:149], v[152:153]
	v_add_f32_e32 v41, 1.0, v41
	v_pk_fma_f32 v[182:183], v[44:45], v[156:157], v[152:153]
	v_cndmask_b32_e32 v165, 0, v165, vcc
	v_cndmask_b32_e32 v164, 0, v164, vcc
	v_rcp_f32_e32 v190, v41
	v_add_f32_e32 v41, 1.0, v191
	v_cndmask_b32_e32 v182, 0, v182, vcc
	v_rcp_f32_e32 v191, v41
	v_mul_f32_e32 v41, 0xbfb8aa3b, v164
	v_mul_f32_e32 v192, 0xbfb8aa3b, v165
	v_exp_f32_e32 v41, v41
	v_exp_f32_e32 v193, v192
	v_mul_f32_e32 v192, 0xbfb8aa3b, v182
	v_pk_fma_f32 v[184:185], v[134:135], v[170:171], v[184:185]
	v_exp_f32_e32 v194, v192
	v_lshlrev_b32_e32 v152, 16, v99
	v_and_b32_e32 v153, 0xffff0000, v99
	v_pk_fma_f32 v[184:185], v[140:141], v[150:151], v[184:185]
	v_add_f32_e32 v41, 1.0, v41
	v_pk_fma_f32 v[184:185], v[142:143], v[152:153], v[184:185]
	v_cndmask_b32_e32 v183, 0, v183, vcc
	v_cndmask_b32_e32 v184, 0, v184, vcc
	v_cndmask_b32_e32 v185, 0, v185, vcc
	v_rcp_f32_e32 v192, v41
	v_add_f32_e32 v41, 1.0, v193
	v_add_f32_e32 v193, 1.0, v194
	v_mul_f32_e32 v195, 0xbfb8aa3b, v184
	v_rcp_f32_e32 v194, v193
	v_mul_f32_e32 v193, 0xbfb8aa3b, v183
	v_exp_f32_e32 v195, v195
	v_mul_f32_e32 v196, 0xbfb8aa3b, v185
	v_exp_f32_e32 v197, v196
	v_exp_f32_e32 v193, v193
	v_add_f32_e32 v195, 1.0, v195
	v_rcp_f32_e32 v196, v195
	v_add_f32_e32 v195, 1.0, v197
	v_add_f32_e32 v193, 1.0, v193
	v_rcp_f32_e32 v197, v195
	v_rcp_f32_e32 v195, v193
	v_rcp_f32_e32 v193, v41
	v_pk_mul_f32 v[188:189], v[188:189], v[190:191]
	v_pk_mul_f32 v[184:185], v[184:185], v[196:197]
	v_pk_mul_f32 v[190:191], v[188:189], v[188:189]
	v_pk_mul_f32 v[164:165], v[164:165], v[192:193]
	v_add_f32_e32 v41, v190, v191
	v_pk_mul_f32 v[192:193], v[164:165], v[164:165]
	v_pk_mul_f32 v[182:183], v[182:183], v[194:195]
	v_add_f32_e32 v41, v192, v41
	v_pk_mul_f32 v[194:195], v[182:183], v[182:183]
	v_add_f32_e32 v41, v193, v41
	v_add_f32_e32 v41, v194, v41
	v_pk_mul_f32 v[196:197], v[184:185], v[184:185]
	v_add_f32_e32 v41, v195, v41
	v_add_f32_e32 v41, v196, v41
	v_add_f32_e32 v41, v197, v41
	v_pk_fma_f32 v[170:171], v[46:47], v[170:171], 0 op_sel_hi:[1,1,0]
	s_nop 0
	v_add_f32_dpp v41, v41, v41 quad_perm:[1,0,3,2] row_mask:0xf bank_mask:0xf bound_ctrl:1
	v_pk_fma_f32 v[170:171], v[134:135], v[150:151], v[170:171]
	v_pk_fma_f32 v[150:151], v[46:47], v[150:151], 0 op_sel_hi:[1,1,0]
	v_add_f32_dpp v41, v41, v41 quad_perm:[2,3,0,1] row_mask:0xf bank_mask:0xf bound_ctrl:1
	v_pk_fma_f32 v[170:171], v[140:141], v[152:153], v[170:171]
	v_pk_fma_f32 v[150:151], v[134:135], v[152:153], v[150:151]
	v_add_f32_dpp v41, v41, v41 row_half_mirror row_mask:0xf bank_mask:0xf bound_ctrl:1
	v_pk_fma_f32 v[152:153], v[46:47], v[152:153], 0 op_sel_hi:[1,1,0]
	s_nop 0
	v_add_f32_dpp v41, v41, v41 row_mirror row_mask:0xf bank_mask:0xf bound_ctrl:1
	v_add_f32_e32 v41, 0x358637bd, v41
	v_rsq_f32_e32 v190, v41
	v_mov_b32_e32 v41, v132
	v_lshl_add_u64 v[186:187], v[186:187], 0, v[40:41]
	global_store_dwordx4 v[186:187], v[178:181], off nt
	v_pk_mul_f32 v[186:187], v[188:189], v[190:191] op_sel_hi:[1,0]
	v_pk_mul_f32 v[164:165], v[164:165], v[190:191] op_sel_hi:[1,0]
	v_pk_mul_f32 v[188:189], v[182:183], v[190:191] op_sel_hi:[1,0]
	v_pk_mul_f32 v[184:185], v[184:185], v[190:191] op_sel_hi:[1,0]
	v_mul_u32_u24_e32 v178, 0x110, v198
	v_cvt_pk_bf16_f32 v180, v186, v187
	v_cvt_pk_bf16_f32 v181, v164, v165
	v_cvt_pk_bf16_f32 v182, v188, v189
	v_cvt_pk_bf16_f32 v183, v184, v185
	v_add3_u32 v178, 0, v178, v40
	ds_write_b128 v178, v[180:183] offset:17408
	v_pk_mul_f32 v[180:181], v[12:13], v[186:187] op_sel:[1,0]
	v_pk_mul_f32 v[182:183], v[12:13], v[164:165] op_sel:[1,0]
	v_cvt_pk_bf16_f32 v180, v180, v181
	v_cvt_pk_bf16_f32 v181, v182, v183
	v_pk_mul_f32 v[182:183], v[12:13], v[188:189] op_sel:[1,0]
	v_pk_mul_f32 v[12:13], v[12:13], v[184:185] op_sel:[1,0]
	v_cvt_pk_bf16_f32 v182, v182, v183
	v_cvt_pk_bf16_f32 v183, v12, v13
	v_pk_mul_f32 v[12:13], v[8:9], v[186:187] op_sel:[1,0]
	ds_write_b128 v178, v[180:183] offset:52224
	v_cvt_pk_bf16_f32 v180, v12, v13
	v_pk_mul_f32 v[12:13], v[8:9], v[164:165] op_sel:[1,0]
	v_lshlrev_b32_e32 v164, 16, v100
	v_cvt_pk_bf16_f32 v181, v12, v13
	v_pk_mul_f32 v[12:13], v[8:9], v[188:189] op_sel:[1,0]
	v_pk_mul_f32 v[8:9], v[8:9], v[184:185] op_sel:[1,0]
	v_and_b32_e32 v165, 0xffff0000, v100
	v_cvt_pk_bf16_f32 v183, v8, v9
	v_pk_fma_f32 v[8:9], v[20:21], v[162:163], 0 op_sel_hi:[1,1,0]
	v_lshlrev_b32_e32 v162, 16, v101
	v_pk_fma_f32 v[8:9], v[22:23], v[144:145], v[8:9]
	v_and_b32_e32 v163, 0xffff0000, v101
	v_pk_fma_f32 v[8:9], v[24:25], v[160:161], v[8:9]
	v_or_b32_e32 v179, 2, v19
	v_pk_fma_f32 v[186:187], v[26:27], v[164:165], v[8:9]
	v_pk_fma_f32 v[8:9], v[28:29], v[166:167], 0 op_sel_hi:[1,1,0]
	v_cmp_gt_u32_e32 vcc, s3, v179
	v_pk_fma_f32 v[8:9], v[30:31], v[146:147], v[8:9]
	v_cvt_pk_bf16_f32 v182, v12, v13
	v_pk_fma_f32 v[8:9], v[32:33], v[158:159], v[8:9]
	v_cndmask_b32_e32 v187, 0, v187, vcc
	v_pk_fma_f32 v[166:167], v[34:35], v[162:163], v[8:9]
	v_pk_fma_f32 v[8:9], v[36:37], v[168:169], 0 op_sel_hi:[1,1,0]
	v_cndmask_b32_e32 v186, 0, v186, vcc
	v_pk_fma_f32 v[8:9], v[38:39], v[148:149], v[8:9]
	v_lshlrev_b32_e32 v12, 16, v102
	v_and_b32_e32 v13, 0xffff0000, v102
	v_pk_fma_f32 v[8:9], v[42:43], v[156:157], v[8:9]
	v_cndmask_b32_e32 v167, 0, v167, vcc
	v_cndmask_b32_e32 v166, 0, v166, vcc
	v_mul_f32_e32 v188, 0xbfb8aa3b, v186
	v_mul_f32_e32 v189, 0xbfb8aa3b, v187
	v_pk_fma_f32 v[168:169], v[44:45], v[12:13], v[8:9]
	v_exp_f32_e32 v188, v188
	v_exp_f32_e32 v189, v189
	v_mul_f32_e32 v190, 0xbfb8aa3b, v166
	v_mul_f32_e32 v191, 0xbfb8aa3b, v167
	v_lshlrev_b32_e32 v8, 16, v103
	v_and_b32_e32 v9, 0xffff0000, v103
	v_cndmask_b32_e32 v169, 0, v169, vcc
	v_cndmask_b32_e32 v168, 0, v168, vcc
	v_exp_f32_e32 v190, v190
	v_exp_f32_e32 v191, v191
	v_pk_fma_f32 v[170:171], v[142:143], v[8:9], v[170:171]
	v_mul_f32_e32 v192, 0xbfb8aa3b, v168
	v_mul_f32_e32 v193, 0xbfb8aa3b, v169
	v_cndmask_b32_e32 v171, 0, v171, vcc
	v_cndmask_b32_e32 v170, 0, v170, vcc
	v_exp_f32_e32 v192, v192
	v_exp_f32_e32 v193, v193
	v_add_f32_e32 v188, 1.0, v188
	v_add_f32_e32 v189, 1.0, v189
	v_mul_f32_e32 v194, 0xbfb8aa3b, v170
	v_mul_f32_e32 v195, 0xbfb8aa3b, v171
	v_rcp_f32_e32 v188, v188
	v_rcp_f32_e32 v189, v189
	v_add_f32_e32 v190, 1.0, v190
	v_add_f32_e32 v191, 1.0, v191
	v_exp_f32_e32 v194, v194
	v_exp_f32_e32 v195, v195
	v_rcp_f32_e32 v190, v190
	v_rcp_f32_e32 v191, v191
	v_add_f32_e32 v192, 1.0, v192
	v_add_f32_e32 v193, 1.0, v193
	v_rcp_f32_e32 v192, v192
	v_rcp_f32_e32 v193, v193
	v_add_f32_e32 v194, 1.0, v194
	v_add_f32_e32 v195, 1.0, v195
	v_pk_mul_f32 v[186:187], v[186:187], v[188:189]
	v_rcp_f32_e32 v194, v194
	v_rcp_f32_e32 v195, v195
	v_pk_mul_f32 v[166:167], v[166:167], v[190:191]
	v_pk_mul_f32 v[188:189], v[186:187], v[186:187]
	v_pk_mul_f32 v[190:191], v[166:167], v[166:167]
	v_add_f32_e32 v188, v188, v189
	v_pk_mul_f32 v[168:169], v[168:169], v[192:193]
	v_add_f32_e32 v188, v190, v188
	v_pk_mul_f32 v[192:193], v[168:169], v[168:169]
	v_add_f32_e32 v188, v191, v188
	v_pk_mul_f32 v[170:171], v[170:171], v[194:195]
	v_add_f32_e32 v188, v192, v188
	v_pk_mul_f32 v[194:195], v[170:171], v[170:171]
	v_add_f32_e32 v188, v193, v188
	v_add_f32_e32 v188, v194, v188
	v_add_f32_e32 v188, v195, v188
	v_lshlrev_b32_e32 v184, 8, v198
	v_mov_b32_e32 v185, v132
	v_add_f32_dpp v188, v188, v188 quad_perm:[1,0,3,2] row_mask:0xf bank_mask:0xf bound_ctrl:1
	v_lshl_add_u64 v[184:185], s[4:5], 0, v[184:185]
	v_lshl_add_u64 v[184:185], v[184:185], 0, v[40:41]
	v_add_f32_dpp v188, v188, v188 quad_perm:[2,3,0,1] row_mask:0xf bank_mask:0xf bound_ctrl:1
	global_store_dwordx4 v[184:185], v[180:183], off nt
	v_pk_fma_f32 v[144:145], v[20:21], v[144:145], 0 op_sel_hi:[1,1,0]
	v_add_f32_dpp v188, v188, v188 row_half_mirror row_mask:0xf bank_mask:0xf bound_ctrl:1
	v_pk_fma_f32 v[144:145], v[22:23], v[160:161], v[144:145]
	v_pk_fma_f32 v[146:147], v[28:29], v[146:147], 0 op_sel_hi:[1,1,0]
	v_add_f32_dpp v188, v188, v188 row_mirror row_mask:0xf bank_mask:0xf bound_ctrl:1
	v_add_f32_e32 v188, 0x358637bd, v188
	v_rsq_f32_e32 v188, v188
	v_pk_fma_f32 v[144:145], v[24:25], v[164:165], v[144:145]
	v_pk_fma_f32 v[146:147], v[30:31], v[158:159], v[146:147]
	v_pk_fma_f32 v[148:149], v[36:37], v[148:149], 0 op_sel_hi:[1,1,0]
	v_pk_mul_f32 v[180:181], v[186:187], v[188:189] op_sel_hi:[1,0]
	v_pk_mul_f32 v[182:183], v[166:167], v[188:189] op_sel_hi:[1,0]
	v_pk_mul_f32 v[184:185], v[168:169], v[188:189] op_sel_hi:[1,0]
	v_pk_mul_f32 v[170:171], v[170:171], v[188:189] op_sel_hi:[1,0]
	v_cvt_pk_bf16_f32 v166, v180, v181
	v_cvt_pk_bf16_f32 v167, v182, v183
	v_cvt_pk_bf16_f32 v168, v184, v185
	v_cvt_pk_bf16_f32 v169, v170, v171
	ds_write_b128 v178, v[166:169] offset:17680
	v_pk_mul_f32 v[166:167], v[14:15], v[180:181] op_sel_hi:[0,1]
	v_pk_mul_f32 v[168:169], v[14:15], v[182:183] op_sel_hi:[0,1]
	v_cvt_pk_bf16_f32 v166, v166, v167
	v_cvt_pk_bf16_f32 v167, v168, v169
	v_pk_mul_f32 v[168:169], v[14:15], v[184:185] op_sel_hi:[0,1]
	v_pk_mul_f32 v[186:187], v[14:15], v[170:171] op_sel_hi:[0,1]
	v_cvt_pk_bf16_f32 v168, v168, v169
	v_cvt_pk_bf16_f32 v169, v186, v187
	ds_write_b128 v178, v[166:169] offset:52496
	v_pk_mul_f32 v[166:167], v[10:11], v[180:181] op_sel_hi:[0,1]
	v_cvt_pk_bf16_f32 v180, v166, v167
	v_pk_mul_f32 v[166:167], v[10:11], v[182:183] op_sel_hi:[0,1]
	v_cvt_pk_bf16_f32 v181, v166, v167
	v_pk_mul_f32 v[166:167], v[10:11], v[184:185] op_sel_hi:[0,1]
	v_cvt_pk_bf16_f32 v182, v166, v167
	v_pk_mul_f32 v[166:167], v[10:11], v[170:171] op_sel_hi:[0,1]
	v_lshlrev_b32_e32 v184, 8, v179
	v_lshlrev_b32_e32 v170, 16, v104
	v_and_b32_e32 v171, 0xffff0000, v104
	v_or_b32_e32 v179, 3, v19
	v_pk_fma_f32 v[144:145], v[26:27], v[170:171], v[144:145]
	v_cmp_gt_u32_e32 vcc, s3, v179
	v_lshlrev_b32_e32 v168, 16, v105
	v_and_b32_e32 v169, 0xffff0000, v105
	v_cndmask_b32_e32 v144, 0, v144, vcc
	v_cndmask_b32_e32 v145, 0, v145, vcc
	v_mul_f32_e32 v10, 0xbfb8aa3b, v144
	v_exp_f32_e32 v10, v10
	v_mul_f32_e32 v14, 0xbfb8aa3b, v145
	v_exp_f32_e32 v14, v14
	v_pk_fma_f32 v[146:147], v[32:33], v[162:163], v[146:147]
	v_pk_fma_f32 v[148:149], v[38:39], v[156:157], v[148:149]
	v_cvt_pk_bf16_f32 v183, v166, v167
	v_pk_fma_f32 v[146:147], v[34:35], v[168:169], v[146:147]
	v_lshlrev_b32_e32 v166, 16, v106
	v_and_b32_e32 v167, 0xffff0000, v106
	v_pk_fma_f32 v[148:149], v[42:43], v[12:13], v[148:149]
	v_add_f32_e32 v10, 1.0, v10
	v_pk_fma_f32 v[186:187], v[44:45], v[166:167], v[148:149]
	v_cndmask_b32_e32 v146, 0, v146, vcc
	v_rcp_f32_e32 v188, v10
	v_add_f32_e32 v10, 1.0, v14
	v_cndmask_b32_e32 v147, 0, v147, vcc
	v_cndmask_b32_e32 v186, 0, v186, vcc
	v_rcp_f32_e32 v189, v10
	v_mul_f32_e32 v10, 0xbfb8aa3b, v146
	v_exp_f32_e32 v10, v10
	v_mul_f32_e32 v14, 0xbfb8aa3b, v147
	v_mul_f32_e32 v190, 0xbfb8aa3b, v186
	v_exp_f32_e32 v14, v14
	v_exp_f32_e32 v191, v190
	v_lshlrev_b32_e32 v148, 16, v107
	v_and_b32_e32 v149, 0xffff0000, v107
	v_pk_fma_f32 v[150:151], v[140:141], v[8:9], v[150:151]
	v_add_f32_e32 v10, 1.0, v10
	v_pk_fma_f32 v[150:151], v[142:143], v[148:149], v[150:151]
	v_rcp_f32_e32 v190, v10
	v_cndmask_b32_e32 v150, 0, v150, vcc
	v_cndmask_b32_e32 v151, 0, v151, vcc
	v_add_f32_e32 v10, 1.0, v14
	v_add_f32_e32 v14, 1.0, v191
	v_mul_f32_e32 v191, 0xbfb8aa3b, v150
	v_exp_f32_e32 v191, v191
	v_mul_f32_e32 v193, 0xbfb8aa3b, v151
	v_cndmask_b32_e32 v187, 0, v187, vcc
	v_exp_f32_e32 v193, v193
	v_rcp_f32_e32 v192, v14
	v_mul_f32_e32 v14, 0xbfb8aa3b, v187
	v_exp_f32_e32 v14, v14
	v_add_f32_e32 v191, 1.0, v191
	v_rcp_f32_e32 v194, v191
	v_add_f32_e32 v191, 1.0, v193
	v_rcp_f32_e32 v195, v191
	v_rcp_f32_e32 v191, v10
	v_add_f32_e32 v14, 1.0, v14
	v_rcp_f32_e32 v193, v14
	v_pk_mul_f32 v[144:145], v[144:145], v[188:189]
	v_pk_mul_f32 v[146:147], v[146:147], v[190:191]
	v_pk_mul_f32 v[188:189], v[144:145], v[144:145]
	v_pk_mul_f32 v[190:191], v[146:147], v[146:147]
	v_add_f32_e32 v10, v188, v189
	v_pk_mul_f32 v[186:187], v[186:187], v[192:193]
	v_add_f32_e32 v10, v190, v10
	v_pk_mul_f32 v[192:193], v[186:187], v[186:187]
	v_add_f32_e32 v10, v191, v10
	v_pk_mul_f32 v[150:151], v[150:151], v[194:195]
	v_add_f32_e32 v10, v192, v10
	v_pk_mul_f32 v[194:195], v[150:151], v[150:151]
	v_add_f32_e32 v10, v193, v10
	v_add_f32_e32 v10, v194, v10
	v_add_f32_e32 v10, v195, v10
	v_mov_b32_e32 v185, v132
	v_lshl_add_u64 v[184:185], s[4:5], 0, v[184:185]
	v_add_f32_dpp v10, v10, v10 quad_perm:[1,0,3,2] row_mask:0xf bank_mask:0xf bound_ctrl:1
	v_lshl_add_u64 v[184:185], v[184:185], 0, v[40:41]
	global_store_dwordx4 v[184:185], v[180:183], off nt
	v_add_f32_dpp v10, v10, v10 quad_perm:[2,3,0,1] row_mask:0xf bank_mask:0xf bound_ctrl:1
	v_pk_fma_f32 v[152:153], v[134:135], v[8:9], v[152:153]
	v_pk_fma_f32 v[8:9], v[46:47], v[8:9], 0 op_sel_hi:[1,1,0]
	v_add_f32_dpp v10, v10, v10 row_half_mirror row_mask:0xf bank_mask:0xf bound_ctrl:1
	v_pk_fma_f32 v[152:153], v[140:141], v[148:149], v[152:153]
	v_pk_fma_f32 v[8:9], v[134:135], v[148:149], v[8:9]
	v_add_f32_dpp v10, v10, v10 row_mirror row_mask:0xf bank_mask:0xf bound_ctrl:1
	v_add_f32_e32 v10, 0x358637bd, v10
	v_rsq_f32_e32 v10, v10
	v_pk_fma_f32 v[148:149], v[46:47], v[148:149], 0 op_sel_hi:[1,1,0]
	v_pk_mul_f32 v[180:181], v[144:145], v[10:11] op_sel_hi:[1,0]
	v_pk_mul_f32 v[182:183], v[146:147], v[10:11] op_sel_hi:[1,0]
	v_pk_mul_f32 v[184:185], v[186:187], v[10:11] op_sel_hi:[1,0]
	v_pk_mul_f32 v[150:151], v[150:151], v[10:11] op_sel_hi:[1,0]
	v_mov_b32_e32 v10, v15
	v_cvt_pk_bf16_f32 v144, v180, v181
	v_cvt_pk_bf16_f32 v145, v182, v183
	v_cvt_pk_bf16_f32 v146, v184, v185
	v_cvt_pk_bf16_f32 v147, v150, v151
	v_pk_mul_f32 v[14:15], v[10:11], v[180:181] op_sel_hi:[0,1]
	ds_write_b128 v178, v[144:147] offset:17952
	v_cvt_pk_bf16_f32 v144, v14, v15
	v_pk_mul_f32 v[14:15], v[10:11], v[182:183] op_sel_hi:[0,1]
	v_cvt_pk_bf16_f32 v145, v14, v15
	v_pk_mul_f32 v[14:15], v[10:11], v[184:185] op_sel_hi:[0,1]
	v_cvt_pk_bf16_f32 v146, v14, v15
	v_pk_mul_f32 v[14:15], v[10:11], v[150:151] op_sel_hi:[0,1]
	v_mov_b32_e32 v10, v11
	v_cvt_pk_bf16_f32 v147, v14, v15
	v_pk_mul_f32 v[14:15], v[10:11], v[180:181] op_sel_hi:[0,1]
	v_cvt_pk_bf16_f32 v180, v14, v15
	v_pk_mul_f32 v[14:15], v[10:11], v[182:183] op_sel_hi:[0,1]
	v_cvt_pk_bf16_f32 v181, v14, v15
	v_pk_mul_f32 v[14:15], v[10:11], v[184:185] op_sel_hi:[0,1]
	v_pk_mul_f32 v[10:11], v[10:11], v[150:151] op_sel_hi:[0,1]
	v_cvt_pk_bf16_f32 v183, v10, v11
	v_pk_fma_f32 v[10:11], v[20:21], v[160:161], 0 op_sel_hi:[1,1,0]
	ds_write_b128 v178, v[144:147] offset:52768
	v_pk_fma_f32 v[10:11], v[22:23], v[164:165], v[10:11]
	v_lshlrev_b32_e32 v146, 16, v108
	v_and_b32_e32 v147, 0xffff0000, v108
	v_pk_fma_f32 v[10:11], v[24:25], v[170:171], v[10:11]
	v_lshlrev_b32_e32 v150, 8, v179
	v_pk_fma_f32 v[160:161], v[26:27], v[146:147], v[10:11]
	v_pk_fma_f32 v[10:11], v[28:29], v[158:159], 0 op_sel_hi:[1,1,0]
	v_lshlrev_b32_e32 v144, 16, v109
	v_pk_fma_f32 v[10:11], v[30:31], v[162:163], v[10:11]
	v_and_b32_e32 v145, 0xffff0000, v109
	v_pk_fma_f32 v[10:11], v[32:33], v[168:169], v[10:11]
	v_or_b32_e32 v179, 4, v19
	v_pk_fma_f32 v[158:159], v[34:35], v[144:145], v[10:11]
	v_pk_fma_f32 v[10:11], v[36:37], v[156:157], 0 op_sel_hi:[1,1,0]
	v_cmp_gt_u32_e32 vcc, s3, v179
	v_pk_fma_f32 v[10:11], v[38:39], v[12:13], v[10:11]
	v_cvt_pk_bf16_f32 v182, v14, v15
	v_cndmask_b32_e32 v161, 0, v161, vcc
	v_cndmask_b32_e32 v160, 0, v160, vcc
	v_lshlrev_b32_e32 v14, 16, v110
	v_and_b32_e32 v15, 0xffff0000, v110
	v_pk_fma_f32 v[10:11], v[42:43], v[166:167], v[10:11]
	v_cndmask_b32_e32 v159, 0, v159, vcc
	v_cndmask_b32_e32 v158, 0, v158, vcc
	v_mul_f32_e32 v184, 0xbfb8aa3b, v160
	v_mul_f32_e32 v185, 0xbfb8aa3b, v161
	v_pk_fma_f32 v[156:157], v[44:45], v[14:15], v[10:11]
	v_exp_f32_e32 v184, v184
	v_exp_f32_e32 v185, v185
	v_mul_f32_e32 v186, 0xbfb8aa3b, v158
	v_mul_f32_e32 v187, 0xbfb8aa3b, v159
	v_lshlrev_b32_e32 v10, 16, v111
	v_and_b32_e32 v11, 0xffff0000, v111
	v_cndmask_b32_e32 v157, 0, v157, vcc
	v_cndmask_b32_e32 v156, 0, v156, vcc
	v_exp_f32_e32 v186, v186
	v_exp_f32_e32 v187, v187
	v_pk_fma_f32 v[152:153], v[142:143], v[10:11], v[152:153]
	v_mul_f32_e32 v188, 0xbfb8aa3b, v156
	v_mul_f32_e32 v189, 0xbfb8aa3b, v157
	v_cndmask_b32_e32 v153, 0, v153, vcc
	v_cndmask_b32_e32 v152, 0, v152, vcc
	v_exp_f32_e32 v188, v188
	v_exp_f32_e32 v189, v189
	v_add_f32_e32 v184, 1.0, v184
	v_add_f32_e32 v185, 1.0, v185
	v_mul_f32_e32 v190, 0xbfb8aa3b, v152
	v_mul_f32_e32 v191, 0xbfb8aa3b, v153
	v_rcp_f32_e32 v184, v184
	v_rcp_f32_e32 v185, v185
	v_add_f32_e32 v186, 1.0, v186
	v_add_f32_e32 v187, 1.0, v187
	v_exp_f32_e32 v190, v190
	v_exp_f32_e32 v191, v191
	v_rcp_f32_e32 v186, v186
	v_rcp_f32_e32 v187, v187
	v_add_f32_e32 v188, 1.0, v188
	v_add_f32_e32 v189, 1.0, v189
	v_rcp_f32_e32 v188, v188
	v_rcp_f32_e32 v189, v189
	v_add_f32_e32 v190, 1.0, v190
	v_add_f32_e32 v191, 1.0, v191
	v_pk_mul_f32 v[160:161], v[160:161], v[184:185]
	v_rcp_f32_e32 v190, v190
	v_rcp_f32_e32 v191, v191
	v_pk_mul_f32 v[158:159], v[158:159], v[186:187]
	v_pk_mul_f32 v[184:185], v[160:161], v[160:161]
	v_pk_mul_f32 v[186:187], v[158:159], v[158:159]
	v_add_f32_e32 v184, v184, v185
	v_pk_mul_f32 v[156:157], v[156:157], v[188:189]
	v_add_f32_e32 v184, v186, v184
	v_pk_mul_f32 v[188:189], v[156:157], v[156:157]
	v_add_f32_e32 v184, v187, v184
	v_pk_mul_f32 v[152:153], v[152:153], v[190:191]
	v_add_f32_e32 v184, v188, v184
	v_pk_mul_f32 v[190:191], v[152:153], v[152:153]
	v_add_f32_e32 v184, v189, v184
	v_add_f32_e32 v184, v190, v184
	v_add_f32_e32 v184, v191, v184
	v_mov_b32_e32 v151, v132
	v_lshl_add_u64 v[150:151], s[4:5], 0, v[150:151]
	v_add_f32_dpp v184, v184, v184 quad_perm:[1,0,3,2] row_mask:0xf bank_mask:0xf bound_ctrl:1
	v_lshl_add_u64 v[150:151], v[150:151], 0, v[40:41]
	global_store_dwordx4 v[150:151], v[180:183], off nt
	v_add_f32_dpp v184, v184, v184 quad_perm:[2,3,0,1] row_mask:0xf bank_mask:0xf bound_ctrl:1
	v_pk_fma_f32 v[12:13], v[36:37], v[12:13], 0 op_sel_hi:[1,1,0]
	v_pk_fma_f32 v[8:9], v[140:141], v[10:11], v[8:9]
	v_add_f32_dpp v184, v184, v184 row_half_mirror row_mask:0xf bank_mask:0xf bound_ctrl:1
	v_pk_fma_f32 v[12:13], v[38:39], v[166:167], v[12:13]
	v_pk_fma_f32 v[166:167], v[36:37], v[166:167], 0 op_sel_hi:[1,1,0]
	v_add_f32_dpp v184, v184, v184 row_mirror row_mask:0xf bank_mask:0xf bound_ctrl:1
	v_add_f32_e32 v184, 0x358637bd, v184
	v_rsq_f32_e32 v184, v184
	v_pk_fma_f32 v[12:13], v[42:43], v[14:15], v[12:13]
	v_pk_fma_f32 v[166:167], v[38:39], v[14:15], v[166:167]
	v_pk_fma_f32 v[148:149], v[134:135], v[10:11], v[148:149]
	v_pk_mul_f32 v[160:161], v[160:161], v[184:185] op_sel_hi:[1,0]
	v_pk_mul_f32 v[180:181], v[158:159], v[184:185] op_sel_hi:[1,0]
	v_pk_mul_f32 v[156:157], v[156:157], v[184:185] op_sel_hi:[1,0]
	v_pk_mul_f32 v[182:183], v[152:153], v[184:185] op_sel_hi:[1,0]
	v_cvt_pk_bf16_f32 v150, v160, v161
	v_cvt_pk_bf16_f32 v151, v180, v181
	v_cvt_pk_bf16_f32 v152, v156, v157
	v_cvt_pk_bf16_f32 v153, v182, v183
	ds_write_b128 v178, v[150:153] offset:18224
	v_pk_mul_f32 v[150:151], v[4:5], v[160:161] op_sel_hi:[0,1]
	v_pk_mul_f32 v[152:153], v[4:5], v[180:181] op_sel_hi:[0,1]
	v_cvt_pk_bf16_f32 v150, v150, v151
	v_cvt_pk_bf16_f32 v151, v152, v153
	v_pk_mul_f32 v[152:153], v[4:5], v[156:157] op_sel_hi:[0,1]
	v_pk_mul_f32 v[158:159], v[4:5], v[182:183] op_sel_hi:[0,1]
	v_cvt_pk_bf16_f32 v152, v152, v153
	v_cvt_pk_bf16_f32 v153, v158, v159
	ds_write_b128 v178, v[150:153] offset:53040
	s_waitcnt lgkmcnt(10)
	v_pk_mul_f32 v[150:151], v[0:1], v[160:161] op_sel_hi:[0,1]
	v_cvt_pk_bf16_f32 v158, v150, v151
	v_pk_mul_f32 v[150:151], v[0:1], v[180:181] op_sel_hi:[0,1]
	v_cvt_pk_bf16_f32 v159, v150, v151
	v_pk_mul_f32 v[150:151], v[0:1], v[156:157] op_sel_hi:[0,1]
	v_cvt_pk_bf16_f32 v160, v150, v151
	v_pk_mul_f32 v[150:151], v[0:1], v[182:183] op_sel_hi:[0,1]
	v_cvt_pk_bf16_f32 v161, v150, v151
	v_pk_fma_f32 v[150:151], v[20:21], v[164:165], 0 op_sel_hi:[1,1,0]
	v_lshlrev_b32_e32 v156, 16, v112
	v_pk_fma_f32 v[150:151], v[22:23], v[170:171], v[150:151]
	v_and_b32_e32 v157, 0xffff0000, v112
	v_pk_fma_f32 v[150:151], v[24:25], v[146:147], v[150:151]
	v_lshlrev_b32_e32 v180, 8, v179
	v_pk_fma_f32 v[164:165], v[26:27], v[156:157], v[150:151]
	v_pk_fma_f32 v[150:151], v[28:29], v[162:163], 0 op_sel_hi:[1,1,0]
	v_or_b32_e32 v179, 5, v19
	v_pk_fma_f32 v[150:151], v[30:31], v[168:169], v[150:151]
	v_lshlrev_b32_e32 v152, 16, v113
	v_and_b32_e32 v153, 0xffff0000, v113
	v_pk_fma_f32 v[150:151], v[32:33], v[144:145], v[150:151]
	v_cmp_gt_u32_e32 vcc, s3, v179
	v_pk_fma_f32 v[162:163], v[34:35], v[152:153], v[150:151]
	v_lshlrev_b32_e32 v150, 16, v114
	v_cndmask_b32_e32 v165, 0, v165, vcc
	v_cndmask_b32_e32 v164, 0, v164, vcc
	v_and_b32_e32 v151, 0xffff0000, v114
	v_cndmask_b32_e32 v163, 0, v163, vcc
	v_cndmask_b32_e32 v162, 0, v162, vcc
	v_mul_f32_e32 v184, 0xbfb8aa3b, v164
	v_mul_f32_e32 v185, 0xbfb8aa3b, v165
	v_pk_fma_f32 v[182:183], v[44:45], v[150:151], v[12:13]
	v_exp_f32_e32 v184, v184
	v_exp_f32_e32 v185, v185
	v_mul_f32_e32 v186, 0xbfb8aa3b, v162
	v_mul_f32_e32 v187, 0xbfb8aa3b, v163
	v_lshlrev_b32_e32 v12, 16, v115
	v_and_b32_e32 v13, 0xffff0000, v115
	v_cndmask_b32_e32 v183, 0, v183, vcc
	v_cndmask_b32_e32 v182, 0, v182, vcc
	v_exp_f32_e32 v186, v186
	v_exp_f32_e32 v187, v187
	v_pk_fma_f32 v[8:9], v[142:143], v[12:13], v[8:9]
	v_mul_f32_e32 v188, 0xbfb8aa3b, v182
	v_mul_f32_e32 v189, 0xbfb8aa3b, v183
	v_cndmask_b32_e32 v9, 0, v9, vcc
	v_cndmask_b32_e32 v8, 0, v8, vcc
	v_exp_f32_e32 v188, v188
	v_exp_f32_e32 v189, v189
	v_add_f32_e32 v184, 1.0, v184
	v_add_f32_e32 v185, 1.0, v185
	v_mul_f32_e32 v190, 0xbfb8aa3b, v8
	v_mul_f32_e32 v191, 0xbfb8aa3b, v9
	v_rcp_f32_e32 v184, v184
	v_rcp_f32_e32 v185, v185
	v_add_f32_e32 v186, 1.0, v186
	v_add_f32_e32 v187, 1.0, v187
	v_exp_f32_e32 v190, v190
	v_exp_f32_e32 v191, v191
	v_rcp_f32_e32 v186, v186
	v_rcp_f32_e32 v187, v187
	v_add_f32_e32 v188, 1.0, v188
	v_add_f32_e32 v189, 1.0, v189
	v_rcp_f32_e32 v188, v188
	v_rcp_f32_e32 v189, v189
	v_add_f32_e32 v190, 1.0, v190
	v_add_f32_e32 v191, 1.0, v191
	v_pk_mul_f32 v[164:165], v[164:165], v[184:185]
	v_rcp_f32_e32 v190, v190
	v_rcp_f32_e32 v191, v191
	v_pk_mul_f32 v[162:163], v[162:163], v[186:187]
	v_pk_mul_f32 v[184:185], v[164:165], v[164:165]
	v_pk_mul_f32 v[186:187], v[162:163], v[162:163]
	v_add_f32_e32 v184, v184, v185
	v_pk_mul_f32 v[182:183], v[182:183], v[188:189]
	v_add_f32_e32 v184, v186, v184
	v_pk_mul_f32 v[188:189], v[182:183], v[182:183]
	v_add_f32_e32 v184, v187, v184
	v_pk_mul_f32 v[8:9], v[8:9], v[190:191]
	v_add_f32_e32 v184, v188, v184
	v_pk_mul_f32 v[190:191], v[8:9], v[8:9]
	v_add_f32_e32 v184, v189, v184
	v_add_f32_e32 v184, v190, v184
	v_add_f32_e32 v184, v191, v184
	v_mov_b32_e32 v181, v132
	v_lshl_add_u64 v[180:181], s[4:5], 0, v[180:181]
	v_add_f32_dpp v184, v184, v184 quad_perm:[1,0,3,2] row_mask:0xf bank_mask:0xf bound_ctrl:1
	v_lshl_add_u64 v[180:181], v[180:181], 0, v[40:41]
	global_store_dwordx4 v[180:181], v[158:161], off nt
	v_add_f32_dpp v184, v184, v184 quad_perm:[2,3,0,1] row_mask:0xf bank_mask:0xf bound_ctrl:1
	v_pk_fma_f32 v[166:167], v[42:43], v[150:151], v[166:167]
	v_pk_fma_f32 v[148:149], v[140:141], v[12:13], v[148:149]
	v_add_f32_dpp v184, v184, v184 row_half_mirror row_mask:0xf bank_mask:0xf bound_ctrl:1
	v_pk_fma_f32 v[14:15], v[36:37], v[14:15], 0 op_sel_hi:[1,1,0]
	v_pk_fma_f32 v[10:11], v[46:47], v[10:11], 0 op_sel_hi:[1,1,0]
	v_add_f32_dpp v184, v184, v184 row_mirror row_mask:0xf bank_mask:0xf bound_ctrl:1
	v_add_f32_e32 v184, 0x358637bd, v184
	v_rsq_f32_e32 v184, v184
	v_pk_fma_f32 v[14:15], v[38:39], v[150:151], v[14:15]
	v_pk_fma_f32 v[10:11], v[134:135], v[12:13], v[10:11]
	v_pk_mul_f32 v[164:165], v[164:165], v[184:185] op_sel_hi:[1,0]
	v_pk_mul_f32 v[162:163], v[162:163], v[184:185] op_sel_hi:[1,0]
	v_pk_mul_f32 v[180:181], v[182:183], v[184:185] op_sel_hi:[1,0]
	v_pk_mul_f32 v[8:9], v[8:9], v[184:185] op_sel_hi:[1,0]
	v_cvt_pk_bf16_f32 v158, v164, v165
	v_cvt_pk_bf16_f32 v159, v162, v163
	v_cvt_pk_bf16_f32 v160, v180, v181
	v_cvt_pk_bf16_f32 v161, v8, v9
	ds_write_b128 v178, v[158:161] offset:18496
	v_pk_mul_f32 v[158:159], v[4:5], v[164:165] op_sel:[1,0]
	v_pk_mul_f32 v[160:161], v[4:5], v[162:163] op_sel:[1,0]
	v_cvt_pk_bf16_f32 v158, v158, v159
	v_cvt_pk_bf16_f32 v159, v160, v161
	v_pk_mul_f32 v[160:161], v[4:5], v[180:181] op_sel:[1,0]
	v_pk_mul_f32 v[4:5], v[4:5], v[8:9] op_sel:[1,0]
	v_cvt_pk_bf16_f32 v160, v160, v161
	v_cvt_pk_bf16_f32 v161, v4, v5
	v_pk_mul_f32 v[4:5], v[0:1], v[164:165] op_sel:[1,0]
	ds_write_b128 v178, v[158:161] offset:53312
	v_cvt_pk_bf16_f32 v158, v4, v5
	v_pk_mul_f32 v[4:5], v[0:1], v[162:163] op_sel:[1,0]
	v_pk_fma_f32 v[164:165], v[28:29], v[168:169], 0 op_sel_hi:[1,1,0]
	v_cvt_pk_bf16_f32 v159, v4, v5
	v_pk_mul_f32 v[4:5], v[0:1], v[180:181] op_sel:[1,0]
	v_pk_mul_f32 v[0:1], v[0:1], v[8:9] op_sel:[1,0]
	v_pk_fma_f32 v[8:9], v[20:21], v[170:171], 0 op_sel_hi:[1,1,0]
	v_cvt_pk_bf16_f32 v160, v4, v5
	v_pk_fma_f32 v[8:9], v[22:23], v[146:147], v[8:9]
	v_cvt_pk_bf16_f32 v161, v0, v1
	v_lshlrev_b32_e32 v0, 8, v179
	v_lshlrev_b32_e32 v4, 16, v116
	v_and_b32_e32 v5, 0xffff0000, v116
	v_pk_fma_f32 v[8:9], v[24:25], v[156:157], v[8:9]
	v_pk_fma_f32 v[164:165], v[30:31], v[144:145], v[164:165]
	v_or_b32_e32 v179, 6, v19
	v_pk_fma_f32 v[8:9], v[26:27], v[4:5], v[8:9]
	v_lshlrev_b32_e32 v162, 16, v117
	v_and_b32_e32 v163, 0xffff0000, v117
	v_pk_fma_f32 v[164:165], v[32:33], v[152:153], v[164:165]
	v_cmp_gt_u32_e32 vcc, s3, v179
	v_pk_fma_f32 v[164:165], v[34:35], v[162:163], v[164:165]
	v_lshlrev_b32_e32 v168, 16, v118
	v_cndmask_b32_e32 v9, 0, v9, vcc
	v_cndmask_b32_e32 v8, 0, v8, vcc
	v_and_b32_e32 v169, 0xffff0000, v118
	v_cndmask_b32_e32 v165, 0, v165, vcc
	v_cndmask_b32_e32 v164, 0, v164, vcc
	v_mul_f32_e32 v180, 0xbfb8aa3b, v8
	v_mul_f32_e32 v181, 0xbfb8aa3b, v9
	v_pk_fma_f32 v[166:167], v[44:45], v[168:169], v[166:167]
	v_exp_f32_e32 v180, v180
	v_exp_f32_e32 v181, v181
	v_mul_f32_e32 v182, 0xbfb8aa3b, v164
	v_mul_f32_e32 v183, 0xbfb8aa3b, v165
	v_lshlrev_b32_e32 v170, 16, v119
	v_and_b32_e32 v171, 0xffff0000, v119
	v_cndmask_b32_e32 v167, 0, v167, vcc
	v_cndmask_b32_e32 v166, 0, v166, vcc
	v_exp_f32_e32 v182, v182
	v_exp_f32_e32 v183, v183
	v_pk_fma_f32 v[148:149], v[142:143], v[170:171], v[148:149]
	v_mul_f32_e32 v184, 0xbfb8aa3b, v166
	v_mul_f32_e32 v185, 0xbfb8aa3b, v167
	v_cndmask_b32_e32 v149, 0, v149, vcc
	v_cndmask_b32_e32 v148, 0, v148, vcc
	v_exp_f32_e32 v184, v184
	v_exp_f32_e32 v185, v185
	v_add_f32_e32 v180, 1.0, v180
	v_add_f32_e32 v181, 1.0, v181
	v_mul_f32_e32 v186, 0xbfb8aa3b, v148
	v_mul_f32_e32 v187, 0xbfb8aa3b, v149
	v_rcp_f32_e32 v180, v180
	v_rcp_f32_e32 v181, v181
	v_add_f32_e32 v182, 1.0, v182
	v_add_f32_e32 v183, 1.0, v183
	v_exp_f32_e32 v186, v186
	v_exp_f32_e32 v187, v187
	v_rcp_f32_e32 v182, v182
	v_rcp_f32_e32 v183, v183
	v_add_f32_e32 v184, 1.0, v184
	v_add_f32_e32 v185, 1.0, v185
	v_rcp_f32_e32 v184, v184
	v_rcp_f32_e32 v185, v185
	v_add_f32_e32 v186, 1.0, v186
	v_add_f32_e32 v187, 1.0, v187
	v_pk_mul_f32 v[8:9], v[8:9], v[180:181]
	v_rcp_f32_e32 v186, v186
	v_rcp_f32_e32 v187, v187
	v_pk_mul_f32 v[164:165], v[164:165], v[182:183]
	v_pk_mul_f32 v[180:181], v[8:9], v[8:9]
	v_pk_mul_f32 v[182:183], v[164:165], v[164:165]
	v_add_f32_e32 v180, v180, v181
	v_pk_mul_f32 v[166:167], v[166:167], v[184:185]
	v_add_f32_e32 v180, v182, v180
	v_pk_mul_f32 v[184:185], v[166:167], v[166:167]
	v_add_f32_e32 v180, v183, v180
	v_pk_mul_f32 v[148:149], v[148:149], v[186:187]
	v_add_f32_e32 v180, v184, v180
	v_pk_mul_f32 v[186:187], v[148:149], v[148:149]
	v_add_f32_e32 v180, v185, v180
	v_add_f32_e32 v180, v186, v180
	v_add_f32_e32 v180, v187, v180
	v_mov_b32_e32 v1, v132
	v_lshl_add_u64 v[0:1], s[4:5], 0, v[0:1]
	v_add_f32_dpp v180, v180, v180 quad_perm:[1,0,3,2] row_mask:0xf bank_mask:0xf bound_ctrl:1
	v_lshl_add_u64 v[0:1], v[0:1], 0, v[40:41]
	global_store_dwordx4 v[0:1], v[158:161], off nt
	v_add_f32_dpp v180, v180, v180 quad_perm:[2,3,0,1] row_mask:0xf bank_mask:0xf bound_ctrl:1
	v_pk_fma_f32 v[20:21], v[20:21], v[146:147], 0 op_sel_hi:[1,1,0]
	v_or_b32_e32 v19, 7, v19
	v_add_f32_dpp v180, v180, v180 row_half_mirror row_mask:0xf bank_mask:0xf bound_ctrl:1
	v_pk_fma_f32 v[20:21], v[22:23], v[156:157], v[20:21]
	v_cmp_gt_u32_e32 vcc, s3, v19
	v_add_f32_dpp v180, v180, v180 row_mirror row_mask:0xf bank_mask:0xf bound_ctrl:1
	v_add_f32_e32 v180, 0x358637bd, v180
	v_rsq_f32_e32 v180, v180
	v_pk_fma_f32 v[4:5], v[24:25], v[4:5], v[20:21]
	v_pk_fma_f32 v[20:21], v[28:29], v[144:145], 0 op_sel_hi:[1,1,0]
	v_pk_fma_f32 v[14:15], v[42:43], v[168:169], v[14:15]
	v_pk_mul_f32 v[0:1], v[8:9], v[180:181] op_sel_hi:[1,0]
	v_pk_mul_f32 v[8:9], v[164:165], v[180:181] op_sel_hi:[1,0]
	v_pk_mul_f32 v[164:165], v[166:167], v[180:181] op_sel_hi:[1,0]
	v_pk_mul_f32 v[148:149], v[148:149], v[180:181] op_sel_hi:[1,0]
	v_cvt_pk_bf16_f32 v158, v0, v1
	v_cvt_pk_bf16_f32 v159, v8, v9
	v_cvt_pk_bf16_f32 v160, v164, v165
	v_cvt_pk_bf16_f32 v161, v148, v149
	ds_write_b128 v178, v[158:161] offset:18768
	v_pk_mul_f32 v[158:159], v[6:7], v[0:1] op_sel_hi:[0,1]
	v_pk_mul_f32 v[160:161], v[6:7], v[8:9] op_sel_hi:[0,1]
	v_cvt_pk_bf16_f32 v158, v158, v159
	v_cvt_pk_bf16_f32 v159, v160, v161
	v_pk_mul_f32 v[160:161], v[6:7], v[164:165] op_sel_hi:[0,1]
	v_pk_mul_f32 v[166:167], v[6:7], v[148:149] op_sel_hi:[0,1]
	v_cvt_pk_bf16_f32 v160, v160, v161
	v_cvt_pk_bf16_f32 v161, v166, v167
	v_pk_mul_f32 v[0:1], v[2:3], v[0:1] op_sel_hi:[0,1]
	ds_write_b128 v178, v[158:161] offset:53584
	v_cvt_pk_bf16_f32 v158, v0, v1
	v_pk_mul_f32 v[0:1], v[2:3], v[8:9] op_sel_hi:[0,1]
	v_lshlrev_b32_e32 v8, 16, v120
	v_and_b32_e32 v9, 0xffff0000, v120
	v_pk_fma_f32 v[4:5], v[26:27], v[8:9], v[4:5]
	v_cvt_pk_bf16_f32 v159, v0, v1
	v_pk_mul_f32 v[0:1], v[2:3], v[164:165] op_sel_hi:[0,1]
	v_cndmask_b32_e32 v4, 0, v4, vcc
	v_cvt_pk_bf16_f32 v160, v0, v1
	v_pk_mul_f32 v[0:1], v[2:3], v[148:149] op_sel_hi:[0,1]
	v_cndmask_b32_e32 v5, 0, v5, vcc
	v_mul_f32_e32 v2, 0xbfb8aa3b, v4
	v_exp_f32_e32 v2, v2
	v_mul_f32_e32 v6, 0xbfb8aa3b, v5
	v_pk_fma_f32 v[20:21], v[30:31], v[152:153], v[20:21]
	v_exp_f32_e32 v6, v6
	v_lshlrev_b32_e32 v8, 16, v121
	v_and_b32_e32 v9, 0xffff0000, v121
	v_pk_fma_f32 v[20:21], v[32:33], v[162:163], v[20:21]
	v_add_f32_e32 v2, 1.0, v2
	v_pk_fma_f32 v[8:9], v[34:35], v[8:9], v[20:21]
	v_lshlrev_b32_e32 v20, 16, v122
	v_and_b32_e32 v21, 0xffff0000, v122
	v_pk_fma_f32 v[14:15], v[44:45], v[20:21], v[14:15]
	v_cndmask_b32_e32 v8, 0, v8, vcc
	v_cndmask_b32_e32 v12, 0, v14, vcc
	v_rcp_f32_e32 v14, v2
	v_add_f32_e32 v2, 1.0, v6
	v_lshlrev_b32_e32 v20, 16, v123
	v_and_b32_e32 v21, 0xffff0000, v123
	v_pk_fma_f32 v[10:11], v[140:141], v[170:171], v[10:11]
	v_cndmask_b32_e32 v9, 0, v9, vcc
	v_cndmask_b32_e32 v13, 0, v15, vcc
	v_rcp_f32_e32 v15, v2
	v_mul_f32_e32 v2, 0xbfb8aa3b, v8
	v_pk_fma_f32 v[10:11], v[142:143], v[20:21], v[10:11]
	v_exp_f32_e32 v2, v2
	v_mul_f32_e32 v6, 0xbfb8aa3b, v9
	v_mul_f32_e32 v20, 0xbfb8aa3b, v12
	v_exp_f32_e32 v6, v6
	v_exp_f32_e32 v21, v20
	v_cndmask_b32_e32 v10, 0, v10, vcc
	v_add_f32_e32 v2, 1.0, v2
	v_cndmask_b32_e32 v11, 0, v11, vcc
	v_rcp_f32_e32 v20, v2
	v_add_f32_e32 v2, 1.0, v6
	v_add_f32_e32 v6, 1.0, v21
	v_mul_f32_e32 v21, 0xbfb8aa3b, v10
	v_exp_f32_e32 v21, v21
	v_mul_f32_e32 v23, 0xbfb8aa3b, v11
	v_exp_f32_e32 v23, v23
	v_rcp_f32_e32 v22, v6
	v_mul_f32_e32 v6, 0xbfb8aa3b, v13
	v_exp_f32_e32 v6, v6
	v_add_f32_e32 v21, 1.0, v21
	v_rcp_f32_e32 v24, v21
	v_add_f32_e32 v21, 1.0, v23
	v_rcp_f32_e32 v25, v21
	v_rcp_f32_e32 v21, v2
	v_add_f32_e32 v6, 1.0, v6
	v_rcp_f32_e32 v23, v6
	v_pk_mul_f32 v[4:5], v[4:5], v[14:15]
	v_pk_mul_f32 v[8:9], v[8:9], v[20:21]
	v_pk_mul_f32 v[14:15], v[4:5], v[4:5]
	v_pk_mul_f32 v[20:21], v[8:9], v[8:9]
	v_add_f32_e32 v2, v14, v15
	v_pk_mul_f32 v[12:13], v[12:13], v[22:23]
	v_add_f32_e32 v2, v20, v2
	v_pk_mul_f32 v[22:23], v[12:13], v[12:13]
	v_add_f32_e32 v2, v21, v2
	v_pk_mul_f32 v[10:11], v[10:11], v[24:25]
	v_add_f32_e32 v2, v22, v2
	v_pk_mul_f32 v[24:25], v[10:11], v[10:11]
	v_add_f32_e32 v2, v23, v2
	v_add_f32_e32 v2, v24, v2
	v_add_f32_e32 v2, v25, v2
	v_cvt_pk_bf16_f32 v161, v0, v1
	v_lshlrev_b32_e32 v0, 8, v179
	v_add_f32_dpp v2, v2, v2 quad_perm:[1,0,3,2] row_mask:0xf bank_mask:0xf bound_ctrl:1
	v_mov_b32_e32 v1, v132
	v_lshl_add_u64 v[0:1], s[4:5], 0, v[0:1]
	v_add_f32_dpp v2, v2, v2 quad_perm:[2,3,0,1] row_mask:0xf bank_mask:0xf bound_ctrl:1
	v_lshl_add_u64 v[0:1], v[0:1], 0, v[40:41]
	global_store_dwordx4 v[0:1], v[158:161], off nt
	v_add_f32_dpp v2, v2, v2 row_half_mirror row_mask:0xf bank_mask:0xf bound_ctrl:1
	s_nop 1
	v_add_f32_dpp v2, v2, v2 row_mirror row_mask:0xf bank_mask:0xf bound_ctrl:1
	v_add_f32_e32 v2, 0x358637bd, v2
	v_rsq_f32_e32 v2, v2
	s_nop 0
	v_pk_mul_f32 v[0:1], v[4:5], v[2:3] op_sel_hi:[1,0]
	v_pk_mul_f32 v[14:15], v[8:9], v[2:3] op_sel_hi:[1,0]
	v_pk_mul_f32 v[12:13], v[12:13], v[2:3] op_sel_hi:[1,0]
	v_pk_mul_f32 v[20:21], v[10:11], v[2:3] op_sel_hi:[1,0]
	v_mov_b32_e32 v2, v7
	v_cvt_pk_bf16_f32 v8, v0, v1
	v_cvt_pk_bf16_f32 v9, v14, v15
	v_cvt_pk_bf16_f32 v10, v12, v13
	v_cvt_pk_bf16_f32 v11, v20, v21
	v_pk_mul_f32 v[4:5], v[2:3], v[0:1] op_sel_hi:[0,1]
	v_pk_mul_f32 v[6:7], v[2:3], v[14:15] op_sel_hi:[0,1]
	ds_write_b128 v178, v[8:11] offset:19040
	v_cvt_pk_bf16_f32 v4, v4, v5
	v_cvt_pk_bf16_f32 v5, v6, v7
	v_pk_mul_f32 v[6:7], v[2:3], v[12:13] op_sel_hi:[0,1]
	v_pk_mul_f32 v[8:9], v[2:3], v[20:21] op_sel_hi:[0,1]
	v_cvt_pk_bf16_f32 v6, v6, v7
	v_cvt_pk_bf16_f32 v7, v8, v9
	ds_write_b128 v178, v[4:7] offset:53856
	v_mov_b32_e32 v4, v3
	v_pk_mul_f32 v[0:1], v[4:5], v[0:1] op_sel_hi:[0,1]
	v_pk_mul_f32 v[2:3], v[4:5], v[14:15] op_sel_hi:[0,1]
	v_cvt_pk_bf16_f32 v0, v0, v1
	v_cvt_pk_bf16_f32 v1, v2, v3
	v_pk_mul_f32 v[2:3], v[4:5], v[12:13] op_sel_hi:[0,1]
	v_pk_mul_f32 v[4:5], v[4:5], v[20:21] op_sel_hi:[0,1]
	v_cvt_pk_bf16_f32 v2, v2, v3
	v_cvt_pk_bf16_f32 v3, v4, v5
	v_lshlrev_b32_e32 v4, 8, v19
	v_mov_b32_e32 v5, v132
	v_lshl_add_u64 v[4:5], s[4:5], 0, v[4:5]
	v_lshl_add_u64 v[4:5], v[4:5], 0, v[40:41]
	global_store_dwordx4 v[4:5], v[0:3], off nt

.LBB0_354:
	s_and_b64 vcc, exec, s[4:5]
	s_cbranch_vccz .LBB0_356
	v_lshlrev_b32_e32 v0, 16, v84
	v_and_b32_e32 v1, 0xffff0000, v84
	v_mov_b32_e32 v8, v48
	v_mov_b32_e32 v9, v52
	v_lshlrev_b32_e32 v144, 16, v80
	v_and_b32_e32 v145, 0xffff0000, v80
	v_pk_fma_f32 v[0:1], v[8:9], v[0:1], 0 op_sel_hi:[1,1,0]
	v_mov_b32_e32 v10, v49
	v_mov_b32_e32 v11, v53
	v_lshlrev_b32_e32 v2, 16, v85
	v_and_b32_e32 v3, 0xffff0000, v85
	v_mov_b32_e32 v20, v56
	v_mov_b32_e32 v21, v60
	v_lshlrev_b32_e32 v152, 16, v88
	v_and_b32_e32 v153, 0xffff0000, v88
	v_pk_fma_f32 v[0:1], v[10:11], v[144:145], v[0:1]
	v_mov_b32_e32 v12, v50
	v_mov_b32_e32 v13, v54
	v_lshlrev_b32_e32 v166, 16, v81
	v_and_b32_e32 v167, 0xffff0000, v81
	v_pk_fma_f32 v[2:3], v[20:21], v[2:3], 0 op_sel_hi:[1,1,0]
	v_mov_b32_e32 v22, v57
	v_mov_b32_e32 v23, v61
	v_lshlrev_b32_e32 v19, 3, v17
	v_lshlrev_b32_e32 v46, 16, v92
	v_and_b32_e32 v47, 0xffff0000, v92
	v_pk_fma_f32 v[0:1], v[12:13], v[152:153], v[0:1]
	v_mov_b32_e32 v14, v51
	v_mov_b32_e32 v15, v55
	v_lshlrev_b32_e32 v160, 16, v89
	v_and_b32_e32 v161, 0xffff0000, v89
	v_pk_fma_f32 v[2:3], v[22:23], v[166:167], v[2:3]
	v_mov_b32_e32 v24, v58
	v_mov_b32_e32 v25, v62
	v_lshlrev_b32_e32 v4, 16, v86
	v_and_b32_e32 v5, 0xffff0000, v86
	v_mov_b32_e32 v28, v64
	v_mov_b32_e32 v29, v68
	v_pk_fma_f32 v[0:1], v[14:15], v[46:47], v[0:1]
	v_lshlrev_b32_e32 v134, 16, v93
	v_and_b32_e32 v135, 0xffff0000, v93
	v_pk_fma_f32 v[2:3], v[24:25], v[160:161], v[2:3]
	v_mov_b32_e32 v26, v59
	v_mov_b32_e32 v27, v63
	v_lshlrev_b32_e32 v168, 16, v82
	v_and_b32_e32 v169, 0xffff0000, v82
	v_pk_fma_f32 v[4:5], v[28:29], v[4:5], 0 op_sel_hi:[1,1,0]
	v_mov_b32_e32 v30, v65
	v_mov_b32_e32 v31, v69
	v_cmp_gt_u32_e32 vcc, s3, v19
	v_pk_fma_f32 v[2:3], v[26:27], v[134:135], v[2:3]
	v_lshlrev_b32_e32 v162, 16, v90
	v_and_b32_e32 v163, 0xffff0000, v90
	v_pk_fma_f32 v[4:5], v[30:31], v[168:169], v[4:5]
	v_mov_b32_e32 v32, v66
	v_mov_b32_e32 v33, v70
	v_lshlrev_b32_e32 v6, 16, v87
	v_and_b32_e32 v7, 0xffff0000, v87
	v_mov_b32_e32 v38, v72
	v_mov_b32_e32 v39, v76
	v_cndmask_b32_e32 v1, 0, v1, vcc
	v_cndmask_b32_e32 v0, 0, v0, vcc
	v_lshlrev_b32_e32 v140, 16, v94
	v_and_b32_e32 v141, 0xffff0000, v94
	v_pk_fma_f32 v[4:5], v[32:33], v[162:163], v[4:5]
	v_mov_b32_e32 v34, v67
	v_mov_b32_e32 v35, v71
	v_lshlrev_b32_e32 v170, 16, v83
	v_and_b32_e32 v171, 0xffff0000, v83
	v_pk_fma_f32 v[6:7], v[38:39], v[6:7], 0 op_sel_hi:[1,1,0]
	v_mov_b32_e32 v40, v73
	v_mov_b32_e32 v41, v77
	v_cndmask_b32_e32 v3, 0, v3, vcc
	v_cndmask_b32_e32 v2, 0, v2, vcc
	v_mul_f32_e32 v36, 0xbfb8aa3b, v0
	v_mul_f32_e32 v37, 0xbfb8aa3b, v1
	v_pk_fma_f32 v[4:5], v[34:35], v[140:141], v[4:5]
	v_lshlrev_b32_e32 v164, 16, v91
	v_and_b32_e32 v165, 0xffff0000, v91
	v_pk_fma_f32 v[6:7], v[40:41], v[170:171], v[6:7]
	v_mov_b32_e32 v42, v74
	v_mov_b32_e32 v43, v78
	v_exp_f32_e32 v36, v36
	v_exp_f32_e32 v37, v37
	v_mul_f32_e32 v146, 0xbfb8aa3b, v2
	v_mul_f32_e32 v147, 0xbfb8aa3b, v3
	v_lshlrev_b32_e32 v142, 16, v95
	v_and_b32_e32 v143, 0xffff0000, v95
	v_pk_fma_f32 v[6:7], v[42:43], v[164:165], v[6:7]
	v_mov_b32_e32 v44, v75
	v_mov_b32_e32 v45, v79
	v_cndmask_b32_e32 v5, 0, v5, vcc
	v_cndmask_b32_e32 v4, 0, v4, vcc
	v_exp_f32_e32 v146, v146
	v_exp_f32_e32 v147, v147
	v_pk_fma_f32 v[6:7], v[44:45], v[142:143], v[6:7]
	v_mul_f32_e32 v148, 0xbfb8aa3b, v4
	v_mul_f32_e32 v149, 0xbfb8aa3b, v5
	v_cndmask_b32_e32 v7, 0, v7, vcc
	v_cndmask_b32_e32 v6, 0, v6, vcc
	v_exp_f32_e32 v148, v148
	v_exp_f32_e32 v149, v149
	v_add_f32_e32 v36, 1.0, v36
	v_add_f32_e32 v37, 1.0, v37
	v_mul_f32_e32 v150, 0xbfb8aa3b, v6
	v_mul_f32_e32 v151, 0xbfb8aa3b, v7
	v_rcp_f32_e32 v36, v36
	v_rcp_f32_e32 v37, v37
	v_add_f32_e32 v146, 1.0, v146
	v_add_f32_e32 v147, 1.0, v147
	v_exp_f32_e32 v150, v150
	v_exp_f32_e32 v151, v151
	v_rcp_f32_e32 v146, v146
	v_rcp_f32_e32 v147, v147
	v_add_f32_e32 v148, 1.0, v148
	v_add_f32_e32 v149, 1.0, v149
	v_rcp_f32_e32 v148, v148
	v_rcp_f32_e32 v149, v149
	v_add_f32_e32 v150, 1.0, v150
	v_add_f32_e32 v151, 1.0, v151
	v_pk_mul_f32 v[36:37], v[0:1], v[36:37]
	v_rcp_f32_e32 v150, v150
	v_rcp_f32_e32 v151, v151
	v_pk_mul_f32 v[146:147], v[2:3], v[146:147]
	v_pk_mul_f32 v[0:1], v[36:37], v[36:37]
	v_pk_mul_f32 v[2:3], v[146:147], v[146:147]
	v_add_f32_e32 v0, v0, v1
	v_pk_mul_f32 v[148:149], v[4:5], v[148:149]
	v_add_f32_e32 v0, v2, v0
	v_pk_mul_f32 v[4:5], v[148:149], v[148:149]
	v_add_f32_e32 v0, v3, v0
	v_pk_mul_f32 v[150:151], v[6:7], v[150:151]
	v_add_f32_e32 v0, v4, v0
	v_pk_mul_f32 v[6:7], v[150:151], v[150:151]
	v_add_f32_e32 v0, v5, v0
	v_add_f32_e32 v0, v6, v0
	v_add_f32_e32 v0, v7, v0
	v_lshl_add_u32 v156, v17, 5, 0
	v_pk_fma_f32 v[144:145], v[8:9], v[144:145], 0 op_sel_hi:[1,1,0]
	v_add_f32_dpp v0, v0, v0 quad_perm:[1,0,3,2] row_mask:0xf bank_mask:0xf bound_ctrl:1
	v_pk_fma_f32 v[144:145], v[10:11], v[152:153], v[144:145]
	v_or_b32_e32 v190, 1, v19
	v_add_f32_dpp v0, v0, v0 quad_perm:[2,3,0,1] row_mask:0xf bank_mask:0xf bound_ctrl:1
	v_pk_fma_f32 v[144:145], v[12:13], v[46:47], v[144:145]
	v_cmp_gt_u32_e32 vcc, s3, v190
	v_add_f32_dpp v0, v0, v0 row_half_mirror row_mask:0xf bank_mask:0xf bound_ctrl:1
	s_lshl_b64 s[4:5], s[40:41], 14
	s_add_u32 s4, s76, s4
	v_add_f32_dpp v0, v0, v0 row_mirror row_mask:0xf bank_mask:0xf bound_ctrl:1
	v_add_f32_e32 v0, 0x358637bd, v0
	v_rsq_f32_e32 v157, v0
	v_add_u32_e32 v0, 0x17a00, v156
	ds_read_b128 v[4:7], v0
	ds_read_b128 v[0:3], v0 offset:16
	s_addc_u32 s5, s77, s5
	v_mul_f32_e32 v156, 0x3db504f3, v157
	v_pk_mul_f32 v[158:159], v[36:37], v[156:157] op_sel_hi:[1,0]
	v_pk_mul_f32 v[178:179], v[146:147], v[156:157] op_sel_hi:[1,0]
	v_pk_mul_f32 v[180:181], v[148:149], v[156:157] op_sel_hi:[1,0]
	v_pk_mul_f32 v[150:151], v[150:151], v[156:157] op_sel_hi:[1,0]
	v_mul_u32_u24_e32 v37, 0x880, v17
	v_lshlrev_b32_e32 v36, 4, v177
	v_cvt_pk_bf16_f32 v146, v158, v159
	v_cvt_pk_bf16_f32 v147, v178, v179
	v_cvt_pk_bf16_f32 v148, v180, v181
	v_cvt_pk_bf16_f32 v149, v150, v151
	v_add3_u32 v37, 0, v37, v36
	ds_write_b128 v37, v[146:149]
	s_waitcnt lgkmcnt(2)
	v_pk_mul_f32 v[146:147], v[4:5], v[158:159] op_sel_hi:[0,1]
	v_cvt_pk_bf16_f32 v156, v146, v147
	v_pk_mul_f32 v[146:147], v[4:5], v[178:179] op_sel_hi:[0,1]
	v_cvt_pk_bf16_f32 v157, v146, v147
	v_pk_mul_f32 v[146:147], v[4:5], v[180:181] op_sel_hi:[0,1]
	v_cvt_pk_bf16_f32 v158, v146, v147
	v_pk_mul_f32 v[146:147], v[4:5], v[150:151] op_sel_hi:[0,1]
	v_lshlrev_b32_e32 v150, 16, v96
	v_and_b32_e32 v151, 0xffff0000, v96
	v_pk_fma_f32 v[180:181], v[14:15], v[150:151], v[144:145]
	v_cvt_pk_bf16_f32 v159, v146, v147
	v_cndmask_b32_e32 v180, 0, v180, vcc
	v_lshlrev_b32_e32 v146, 11, v17
	v_pk_fma_f32 v[144:145], v[20:21], v[166:167], 0 op_sel_hi:[1,1,0]
	v_cndmask_b32_e32 v181, 0, v181, vcc
	v_mul_f32_e32 v17, 0xbfb8aa3b, v180
	v_pk_fma_f32 v[144:145], v[22:23], v[160:161], v[144:145]
	v_exp_f32_e32 v17, v17
	v_mul_f32_e32 v37, 0xbfb8aa3b, v181
	v_lshlrev_b32_e32 v148, 16, v97
	v_and_b32_e32 v149, 0xffff0000, v97
	v_pk_fma_f32 v[144:145], v[24:25], v[134:135], v[144:145]
	v_exp_f32_e32 v37, v37
	v_pk_fma_f32 v[166:167], v[26:27], v[148:149], v[144:145]
	v_pk_fma_f32 v[144:145], v[28:29], v[168:169], 0 op_sel_hi:[1,1,0]
	v_mov_b32_e32 v147, v132
	v_pk_fma_f32 v[144:145], v[30:31], v[162:163], v[144:145]
	v_lshl_add_u64 v[178:179], s[4:5], 0, v[146:147]
	v_lshlrev_b32_e32 v146, 16, v98
	v_and_b32_e32 v147, 0xffff0000, v98
	v_pk_fma_f32 v[144:145], v[32:33], v[140:141], v[144:145]
	v_add_f32_e32 v17, 1.0, v17
	v_pk_fma_f32 v[168:169], v[34:35], v[146:147], v[144:145]
	v_cndmask_b32_e32 v166, 0, v166, vcc
	v_rcp_f32_e32 v182, v17
	v_add_f32_e32 v17, 1.0, v37
	v_cndmask_b32_e32 v167, 0, v167, vcc
	v_cndmask_b32_e32 v168, 0, v168, vcc
	v_rcp_f32_e32 v183, v17
	v_mul_f32_e32 v17, 0xbfb8aa3b, v166
	v_pk_fma_f32 v[170:171], v[38:39], v[170:171], 0 op_sel_hi:[1,1,0]
	v_exp_f32_e32 v17, v17
	v_mul_f32_e32 v37, 0xbfb8aa3b, v167
	v_mul_f32_e32 v184, 0xbfb8aa3b, v168
	v_pk_fma_f32 v[170:171], v[40:41], v[164:165], v[170:171]
	v_exp_f32_e32 v37, v37
	v_exp_f32_e32 v185, v184
	v_lshlrev_b32_e32 v144, 16, v99
	v_and_b32_e32 v145, 0xffff0000, v99
	v_pk_fma_f32 v[170:171], v[42:43], v[142:143], v[170:171]
	v_add_f32_e32 v17, 1.0, v17
	v_pk_fma_f32 v[170:171], v[44:45], v[144:145], v[170:171]
	v_rcp_f32_e32 v184, v17
	v_cndmask_b32_e32 v170, 0, v170, vcc
	v_cndmask_b32_e32 v171, 0, v171, vcc
	v_add_f32_e32 v17, 1.0, v37
	v_add_f32_e32 v37, 1.0, v185
	v_mul_f32_e32 v185, 0xbfb8aa3b, v170
	v_exp_f32_e32 v185, v185
	v_mul_f32_e32 v187, 0xbfb8aa3b, v171
	v_cndmask_b32_e32 v169, 0, v169, vcc
	v_exp_f32_e32 v187, v187
	v_rcp_f32_e32 v186, v37
	v_mul_f32_e32 v37, 0xbfb8aa3b, v169
	v_exp_f32_e32 v37, v37
	v_add_f32_e32 v185, 1.0, v185
	v_rcp_f32_e32 v188, v185
	v_add_f32_e32 v185, 1.0, v187
	v_rcp_f32_e32 v189, v185
	v_rcp_f32_e32 v185, v17
	v_add_f32_e32 v37, 1.0, v37
	v_rcp_f32_e32 v187, v37
	v_pk_mul_f32 v[180:181], v[180:181], v[182:183]
	v_pk_mul_f32 v[166:167], v[166:167], v[184:185]
	v_pk_mul_f32 v[182:183], v[180:181], v[180:181]
	v_pk_mul_f32 v[184:185], v[166:167], v[166:167]
	v_add_f32_e32 v17, v182, v183
	v_pk_mul_f32 v[168:169], v[168:169], v[186:187]
	v_add_f32_e32 v17, v184, v17
	v_pk_mul_f32 v[186:187], v[168:169], v[168:169]
	v_add_f32_e32 v17, v185, v17
	v_pk_mul_f32 v[170:171], v[170:171], v[188:189]
	v_add_f32_e32 v17, v186, v17
	v_pk_mul_f32 v[188:189], v[170:171], v[170:171]
	v_add_f32_e32 v17, v187, v17
	v_add_f32_e32 v17, v188, v17
	v_add_f32_e32 v17, v189, v17
	v_mov_b32_e32 v37, v132
	v_lshl_add_u64 v[178:179], v[178:179], 0, v[36:37]
	v_add_f32_dpp v17, v17, v17 quad_perm:[1,0,3,2] row_mask:0xf bank_mask:0xf bound_ctrl:1
	global_store_dwordx4 v[178:179], v[156:159], off nt
	v_or_b32_e32 v188, 2, v19
	v_add_f32_dpp v17, v17, v17 quad_perm:[2,3,0,1] row_mask:0xf bank_mask:0xf bound_ctrl:1
	v_cmp_gt_u32_e32 vcc, s3, v188
	v_pk_fma_f32 v[164:165], v[38:39], v[164:165], 0 op_sel_hi:[1,1,0]
	v_add_f32_dpp v17, v17, v17 row_half_mirror row_mask:0xf bank_mask:0xf bound_ctrl:1
	v_pk_fma_f32 v[164:165], v[40:41], v[142:143], v[164:165]
	v_pk_fma_f32 v[142:143], v[38:39], v[142:143], 0 op_sel_hi:[1,1,0]
	v_add_f32_dpp v17, v17, v17 row_mirror row_mask:0xf bank_mask:0xf bound_ctrl:1
	v_add_f32_e32 v17, 0x358637bd, v17
	v_rsq_f32_e32 v17, v17
	v_pk_fma_f32 v[164:165], v[42:43], v[144:145], v[164:165]
	v_pk_fma_f32 v[142:143], v[40:41], v[144:145], v[142:143]
	v_pk_fma_f32 v[144:145], v[38:39], v[144:145], 0 op_sel_hi:[1,1,0]
	v_mul_f32_e32 v156, 0x3db504f3, v17
	v_pk_mul_f32 v[178:179], v[180:181], v[156:157] op_sel_hi:[1,0]
	v_pk_mul_f32 v[180:181], v[166:167], v[156:157] op_sel_hi:[1,0]
	v_pk_mul_f32 v[168:169], v[168:169], v[156:157] op_sel_hi:[1,0]
	v_pk_mul_f32 v[170:171], v[170:171], v[156:157] op_sel_hi:[1,0]
	v_mul_u32_u24_e32 v17, 0x110, v190
	v_cvt_pk_bf16_f32 v156, v178, v179
	v_cvt_pk_bf16_f32 v157, v180, v181
	v_cvt_pk_bf16_f32 v158, v168, v169
	v_cvt_pk_bf16_f32 v159, v170, v171
	v_add3_u32 v17, 0, v17, v36
	ds_write_b128 v17, v[156:159]
	v_pk_mul_f32 v[156:157], v[4:5], v[178:179] op_sel:[1,0]
	v_lshlrev_b32_e32 v158, 16, v100
	v_cvt_pk_bf16_f32 v166, v156, v157
	v_pk_mul_f32 v[156:157], v[4:5], v[180:181] op_sel:[1,0]
	v_and_b32_e32 v159, 0xffff0000, v100
	v_cvt_pk_bf16_f32 v167, v156, v157
	v_pk_mul_f32 v[156:157], v[4:5], v[168:169] op_sel:[1,0]
	v_pk_mul_f32 v[4:5], v[4:5], v[170:171] op_sel:[1,0]
	v_cvt_pk_bf16_f32 v168, v156, v157
	v_cvt_pk_bf16_f32 v169, v4, v5
	v_pk_fma_f32 v[4:5], v[8:9], v[152:153], 0 op_sel_hi:[1,1,0]
	v_lshlrev_b32_e32 v156, 16, v101
	v_pk_fma_f32 v[4:5], v[10:11], v[46:47], v[4:5]
	v_and_b32_e32 v157, 0xffff0000, v101
	v_pk_fma_f32 v[4:5], v[12:13], v[150:151], v[4:5]
	v_lshlrev_b32_e32 v152, 16, v102
	v_pk_fma_f32 v[178:179], v[14:15], v[158:159], v[4:5]
	v_pk_fma_f32 v[4:5], v[20:21], v[160:161], 0 op_sel_hi:[1,1,0]
	v_cndmask_b32_e32 v179, 0, v179, vcc
	v_pk_fma_f32 v[4:5], v[22:23], v[134:135], v[4:5]
	v_cndmask_b32_e32 v178, 0, v178, vcc
	v_pk_fma_f32 v[4:5], v[24:25], v[148:149], v[4:5]
	v_and_b32_e32 v153, 0xffff0000, v102
	v_pk_fma_f32 v[160:161], v[26:27], v[156:157], v[4:5]
	v_pk_fma_f32 v[4:5], v[28:29], v[162:163], 0 op_sel_hi:[1,1,0]
	v_cndmask_b32_e32 v161, 0, v161, vcc
	v_pk_fma_f32 v[4:5], v[30:31], v[140:141], v[4:5]
	v_cndmask_b32_e32 v160, 0, v160, vcc
	v_pk_fma_f32 v[4:5], v[32:33], v[146:147], v[4:5]
	v_mul_f32_e32 v180, 0xbfb8aa3b, v178
	v_mul_f32_e32 v181, 0xbfb8aa3b, v179
	v_pk_fma_f32 v[162:163], v[34:35], v[152:153], v[4:5]
	v_exp_f32_e32 v180, v180
	v_exp_f32_e32 v181, v181
	v_mul_f32_e32 v182, 0xbfb8aa3b, v160
	v_mul_f32_e32 v183, 0xbfb8aa3b, v161
	v_lshlrev_b32_e32 v4, 16, v103
	v_and_b32_e32 v5, 0xffff0000, v103
	v_cndmask_b32_e32 v163, 0, v163, vcc
	v_cndmask_b32_e32 v162, 0, v162, vcc
	v_exp_f32_e32 v182, v182
	v_exp_f32_e32 v183, v183
	v_pk_fma_f32 v[164:165], v[44:45], v[4:5], v[164:165]
	v_mul_f32_e32 v184, 0xbfb8aa3b, v162
	v_mul_f32_e32 v185, 0xbfb8aa3b, v163
	v_cndmask_b32_e32 v165, 0, v165, vcc
	v_cndmask_b32_e32 v164, 0, v164, vcc
	v_exp_f32_e32 v184, v184
	v_exp_f32_e32 v185, v185
	v_add_f32_e32 v180, 1.0, v180
	v_add_f32_e32 v181, 1.0, v181
	v_mul_f32_e32 v186, 0xbfb8aa3b, v164
	v_mul_f32_e32 v187, 0xbfb8aa3b, v165
	v_rcp_f32_e32 v180, v180
	v_rcp_f32_e32 v181, v181
	v_add_f32_e32 v182, 1.0, v182
	v_add_f32_e32 v183, 1.0, v183
	v_exp_f32_e32 v186, v186
	v_exp_f32_e32 v187, v187
	v_rcp_f32_e32 v182, v182
	v_rcp_f32_e32 v183, v183
	v_add_f32_e32 v184, 1.0, v184
	v_add_f32_e32 v185, 1.0, v185
	v_rcp_f32_e32 v184, v184
	v_rcp_f32_e32 v185, v185
	v_add_f32_e32 v186, 1.0, v186
	v_add_f32_e32 v187, 1.0, v187
	v_pk_mul_f32 v[178:179], v[178:179], v[180:181]
	v_rcp_f32_e32 v186, v186
	v_rcp_f32_e32 v187, v187
	v_pk_mul_f32 v[160:161], v[160:161], v[182:183]
	v_pk_mul_f32 v[180:181], v[178:179], v[178:179]
	v_pk_mul_f32 v[182:183], v[160:161], v[160:161]
	v_add_f32_e32 v180, v180, v181
	v_pk_mul_f32 v[162:163], v[162:163], v[184:185]
	v_add_f32_e32 v180, v182, v180
	v_pk_mul_f32 v[184:185], v[162:163], v[162:163]
	v_add_f32_e32 v180, v183, v180
	v_pk_mul_f32 v[164:165], v[164:165], v[186:187]
	v_add_f32_e32 v180, v184, v180
	v_pk_mul_f32 v[186:187], v[164:165], v[164:165]
	v_add_f32_e32 v180, v185, v180
	v_add_f32_e32 v180, v186, v180
	v_add_f32_e32 v180, v187, v180
	v_lshlrev_b32_e32 v170, 8, v190
	v_mov_b32_e32 v171, v132
	v_add_f32_dpp v180, v180, v180 quad_perm:[1,0,3,2] row_mask:0xf bank_mask:0xf bound_ctrl:1
	v_lshl_add_u64 v[170:171], s[4:5], 0, v[170:171]
	v_lshl_add_u64 v[170:171], v[170:171], 0, v[36:37]
	v_add_f32_dpp v180, v180, v180 quad_perm:[2,3,0,1] row_mask:0xf bank_mask:0xf bound_ctrl:1
	global_store_dwordx4 v[170:171], v[166:169], off nt
	v_pk_fma_f32 v[46:47], v[8:9], v[46:47], 0 op_sel_hi:[1,1,0]
	v_add_f32_dpp v180, v180, v180 row_half_mirror row_mask:0xf bank_mask:0xf bound_ctrl:1
	v_pk_fma_f32 v[46:47], v[10:11], v[150:151], v[46:47]
	v_pk_fma_f32 v[134:135], v[20:21], v[134:135], 0 op_sel_hi:[1,1,0]
	v_add_f32_dpp v180, v180, v180 row_mirror row_mask:0xf bank_mask:0xf bound_ctrl:1
	v_add_f32_e32 v180, 0x358637bd, v180
	v_rsq_f32_e32 v180, v180
	v_pk_fma_f32 v[46:47], v[12:13], v[158:159], v[46:47]
	v_pk_fma_f32 v[134:135], v[22:23], v[148:149], v[134:135]
	v_pk_fma_f32 v[140:141], v[28:29], v[140:141], 0 op_sel_hi:[1,1,0]
	v_mul_f32_e32 v166, 0x3db504f3, v180
	v_pk_mul_f32 v[168:169], v[178:179], v[166:167] op_sel_hi:[1,0]
	v_pk_mul_f32 v[170:171], v[160:161], v[166:167] op_sel_hi:[1,0]
	v_pk_mul_f32 v[178:179], v[162:163], v[166:167] op_sel_hi:[1,0]
	v_pk_mul_f32 v[164:165], v[164:165], v[166:167] op_sel_hi:[1,0]
	v_cvt_pk_bf16_f32 v160, v168, v169
	v_cvt_pk_bf16_f32 v161, v170, v171
	v_cvt_pk_bf16_f32 v162, v178, v179
	v_cvt_pk_bf16_f32 v163, v164, v165
	ds_write_b128 v17, v[160:163] offset:272
	v_pk_mul_f32 v[160:161], v[6:7], v[168:169] op_sel_hi:[0,1]
	v_cvt_pk_bf16_f32 v168, v160, v161
	v_pk_mul_f32 v[160:161], v[6:7], v[170:171] op_sel_hi:[0,1]
	v_cvt_pk_bf16_f32 v169, v160, v161
	v_pk_mul_f32 v[160:161], v[6:7], v[178:179] op_sel_hi:[0,1]
	v_lshlrev_b32_e32 v178, 8, v188
	v_lshlrev_b32_e32 v166, 16, v104
	v_and_b32_e32 v167, 0xffff0000, v104
	v_or_b32_e32 v188, 3, v19
	v_pk_fma_f32 v[46:47], v[14:15], v[166:167], v[46:47]
	v_cmp_gt_u32_e32 vcc, s3, v188
	v_cvt_pk_bf16_f32 v170, v160, v161
	v_pk_mul_f32 v[160:161], v[6:7], v[164:165] op_sel_hi:[0,1]
	v_cndmask_b32_e32 v46, 0, v46, vcc
	v_cndmask_b32_e32 v47, 0, v47, vcc
	v_mul_f32_e32 v6, 0xbfb8aa3b, v46
	v_exp_f32_e32 v6, v6
	v_mul_f32_e32 v180, 0xbfb8aa3b, v47
	v_exp_f32_e32 v181, v180
	v_lshlrev_b32_e32 v164, 16, v105
	v_and_b32_e32 v165, 0xffff0000, v105
	v_pk_fma_f32 v[134:135], v[24:25], v[156:157], v[134:135]
	v_pk_fma_f32 v[140:141], v[30:31], v[146:147], v[140:141]
	v_pk_fma_f32 v[134:135], v[26:27], v[164:165], v[134:135]
	v_lshlrev_b32_e32 v162, 16, v106
	v_and_b32_e32 v163, 0xffff0000, v106
	v_pk_fma_f32 v[140:141], v[32:33], v[152:153], v[140:141]
	v_add_f32_e32 v6, 1.0, v6
	v_pk_fma_f32 v[140:141], v[34:35], v[162:163], v[140:141]
	v_cndmask_b32_e32 v135, 0, v135, vcc
	v_cndmask_b32_e32 v134, 0, v134, vcc
	v_rcp_f32_e32 v180, v6
	v_add_f32_e32 v6, 1.0, v181
	v_cndmask_b32_e32 v140, 0, v140, vcc
	v_rcp_f32_e32 v181, v6
	v_mul_f32_e32 v6, 0xbfb8aa3b, v134
	v_mul_f32_e32 v182, 0xbfb8aa3b, v135
	v_exp_f32_e32 v6, v6
	v_exp_f32_e32 v183, v182
	v_mul_f32_e32 v182, 0xbfb8aa3b, v140
	v_exp_f32_e32 v184, v182
	v_cvt_pk_bf16_f32 v171, v160, v161
	v_lshlrev_b32_e32 v160, 16, v107
	v_and_b32_e32 v161, 0xffff0000, v107
	v_pk_fma_f32 v[142:143], v[42:43], v[4:5], v[142:143]
	v_add_f32_e32 v6, 1.0, v6
	v_pk_fma_f32 v[142:143], v[44:45], v[160:161], v[142:143]
	v_cndmask_b32_e32 v141, 0, v141, vcc
	v_cndmask_b32_e32 v142, 0, v142, vcc
	v_cndmask_b32_e32 v143, 0, v143, vcc
	v_rcp_f32_e32 v182, v6
	v_add_f32_e32 v6, 1.0, v183
	v_add_f32_e32 v183, 1.0, v184
	v_mul_f32_e32 v185, 0xbfb8aa3b, v142
	v_rcp_f32_e32 v184, v183
	v_mul_f32_e32 v183, 0xbfb8aa3b, v141
	v_exp_f32_e32 v185, v185
	v_mul_f32_e32 v186, 0xbfb8aa3b, v143
	v_exp_f32_e32 v187, v186
	v_exp_f32_e32 v183, v183
	v_add_f32_e32 v185, 1.0, v185
	v_rcp_f32_e32 v186, v185
	v_add_f32_e32 v185, 1.0, v187
	v_add_f32_e32 v183, 1.0, v183
	v_rcp_f32_e32 v187, v185
	v_rcp_f32_e32 v185, v183
	v_rcp_f32_e32 v183, v6
	v_pk_mul_f32 v[46:47], v[46:47], v[180:181]
	v_pk_mul_f32 v[142:143], v[142:143], v[186:187]
	v_pk_mul_f32 v[180:181], v[46:47], v[46:47]
	v_pk_mul_f32 v[134:135], v[134:135], v[182:183]
	v_add_f32_e32 v6, v180, v181
	v_pk_mul_f32 v[182:183], v[134:135], v[134:135]
	v_pk_mul_f32 v[140:141], v[140:141], v[184:185]
	v_add_f32_e32 v6, v182, v6
	v_pk_mul_f32 v[184:185], v[140:141], v[140:141]
	v_add_f32_e32 v6, v183, v6
	v_add_f32_e32 v6, v184, v6
	v_pk_mul_f32 v[186:187], v[142:143], v[142:143]
	v_add_f32_e32 v6, v185, v6
	v_add_f32_e32 v6, v186, v6
	v_add_f32_e32 v6, v187, v6
	v_mov_b32_e32 v179, v132
	v_lshl_add_u64 v[178:179], s[4:5], 0, v[178:179]
	v_add_f32_dpp v6, v6, v6 quad_perm:[1,0,3,2] row_mask:0xf bank_mask:0xf bound_ctrl:1
	v_lshl_add_u64 v[178:179], v[178:179], 0, v[36:37]
	global_store_dwordx4 v[178:179], v[168:171], off nt
	v_add_f32_dpp v6, v6, v6 quad_perm:[2,3,0,1] row_mask:0xf bank_mask:0xf bound_ctrl:1
	v_or_b32_e32 v186, 4, v19
	v_cmp_gt_u32_e32 vcc, s3, v186
	v_add_f32_dpp v6, v6, v6 row_half_mirror row_mask:0xf bank_mask:0xf bound_ctrl:1
	v_pk_fma_f32 v[144:145], v[40:41], v[4:5], v[144:145]
	v_pk_fma_f32 v[4:5], v[38:39], v[4:5], 0 op_sel_hi:[1,1,0]
	v_add_f32_dpp v6, v6, v6 row_mirror row_mask:0xf bank_mask:0xf bound_ctrl:1
	v_add_f32_e32 v6, 0x358637bd, v6
	v_rsq_f32_e32 v6, v6
	v_pk_fma_f32 v[144:145], v[42:43], v[160:161], v[144:145]
	v_pk_fma_f32 v[4:5], v[40:41], v[160:161], v[4:5]
	v_pk_fma_f32 v[160:161], v[38:39], v[160:161], 0 op_sel_hi:[1,1,0]
	v_mul_f32_e32 v6, 0x3db504f3, v6
	v_pk_mul_f32 v[46:47], v[46:47], v[6:7] op_sel_hi:[1,0]
	v_pk_mul_f32 v[134:135], v[134:135], v[6:7] op_sel_hi:[1,0]
	v_pk_mul_f32 v[170:171], v[140:141], v[6:7] op_sel_hi:[1,0]
	v_pk_mul_f32 v[178:179], v[142:143], v[6:7] op_sel_hi:[1,0]
	v_mov_b32_e32 v6, v7
	v_cvt_pk_bf16_f32 v140, v46, v47
	v_pk_mul_f32 v[46:47], v[6:7], v[46:47] op_sel_hi:[0,1]
	v_cvt_pk_bf16_f32 v168, v46, v47
	v_pk_mul_f32 v[46:47], v[6:7], v[134:135] op_sel_hi:[0,1]
	v_cvt_pk_bf16_f32 v169, v46, v47
	v_pk_mul_f32 v[46:47], v[6:7], v[170:171] op_sel_hi:[0,1]
	v_pk_mul_f32 v[6:7], v[6:7], v[178:179] op_sel_hi:[0,1]
	v_cvt_pk_bf16_f32 v142, v170, v171
	v_cvt_pk_bf16_f32 v171, v6, v7
	v_pk_fma_f32 v[6:7], v[8:9], v[150:151], 0 op_sel_hi:[1,1,0]
	v_cvt_pk_bf16_f32 v141, v134, v135
	v_cvt_pk_bf16_f32 v143, v178, v179
	v_pk_fma_f32 v[6:7], v[10:11], v[158:159], v[6:7]
	ds_write_b128 v17, v[140:143] offset:544
	v_lshlrev_b32_e32 v140, 16, v108
	v_and_b32_e32 v141, 0xffff0000, v108
	v_pk_fma_f32 v[6:7], v[12:13], v[166:167], v[6:7]
	v_lshlrev_b32_e32 v134, 16, v109
	v_pk_fma_f32 v[150:151], v[14:15], v[140:141], v[6:7]
	v_pk_fma_f32 v[6:7], v[20:21], v[148:149], 0 op_sel_hi:[1,1,0]
	v_and_b32_e32 v135, 0xffff0000, v109
	v_pk_fma_f32 v[6:7], v[22:23], v[156:157], v[6:7]
	v_cndmask_b32_e32 v151, 0, v151, vcc
	v_pk_fma_f32 v[6:7], v[24:25], v[164:165], v[6:7]
	v_cndmask_b32_e32 v150, 0, v150, vcc
	v_pk_fma_f32 v[148:149], v[26:27], v[134:135], v[6:7]
	v_pk_fma_f32 v[6:7], v[28:29], v[146:147], 0 op_sel_hi:[1,1,0]
	v_cvt_pk_bf16_f32 v170, v46, v47
	v_pk_fma_f32 v[6:7], v[30:31], v[152:153], v[6:7]
	v_lshlrev_b32_e32 v46, 16, v110
	v_and_b32_e32 v47, 0xffff0000, v110
	v_pk_fma_f32 v[6:7], v[32:33], v[162:163], v[6:7]
	v_cndmask_b32_e32 v149, 0, v149, vcc
	v_cndmask_b32_e32 v148, 0, v148, vcc
	v_mul_f32_e32 v178, 0xbfb8aa3b, v150
	v_mul_f32_e32 v179, 0xbfb8aa3b, v151
	v_pk_fma_f32 v[146:147], v[34:35], v[46:47], v[6:7]
	v_exp_f32_e32 v178, v178
	v_exp_f32_e32 v179, v179
	v_mul_f32_e32 v180, 0xbfb8aa3b, v148
	v_mul_f32_e32 v181, 0xbfb8aa3b, v149
	v_lshlrev_b32_e32 v6, 16, v111
	v_and_b32_e32 v7, 0xffff0000, v111
	v_cndmask_b32_e32 v147, 0, v147, vcc
	v_cndmask_b32_e32 v146, 0, v146, vcc
	v_exp_f32_e32 v180, v180
	v_exp_f32_e32 v181, v181
	v_pk_fma_f32 v[144:145], v[44:45], v[6:7], v[144:145]
	v_mul_f32_e32 v182, 0xbfb8aa3b, v146
	v_mul_f32_e32 v183, 0xbfb8aa3b, v147
	v_cndmask_b32_e32 v145, 0, v145, vcc
	v_cndmask_b32_e32 v144, 0, v144, vcc
	v_exp_f32_e32 v182, v182
	v_exp_f32_e32 v183, v183
	v_add_f32_e32 v178, 1.0, v178
	v_add_f32_e32 v179, 1.0, v179
	v_mul_f32_e32 v184, 0xbfb8aa3b, v144
	v_mul_f32_e32 v185, 0xbfb8aa3b, v145
	v_rcp_f32_e32 v178, v178
	v_rcp_f32_e32 v179, v179
	v_add_f32_e32 v180, 1.0, v180
	v_add_f32_e32 v181, 1.0, v181
	v_exp_f32_e32 v184, v184
	v_exp_f32_e32 v185, v185
	v_rcp_f32_e32 v180, v180
	v_rcp_f32_e32 v181, v181
	v_add_f32_e32 v182, 1.0, v182
	v_add_f32_e32 v183, 1.0, v183
	v_rcp_f32_e32 v182, v182
	v_rcp_f32_e32 v183, v183
	v_add_f32_e32 v184, 1.0, v184
	v_add_f32_e32 v185, 1.0, v185
	v_pk_mul_f32 v[150:151], v[150:151], v[178:179]
	v_rcp_f32_e32 v184, v184
	v_rcp_f32_e32 v185, v185
	v_pk_mul_f32 v[148:149], v[148:149], v[180:181]
	v_pk_mul_f32 v[178:179], v[150:151], v[150:151]
	v_pk_mul_f32 v[180:181], v[148:149], v[148:149]
	v_add_f32_e32 v178, v178, v179
	v_pk_mul_f32 v[146:147], v[146:147], v[182:183]
	v_add_f32_e32 v178, v180, v178
	v_pk_mul_f32 v[182:183], v[146:147], v[146:147]
	v_add_f32_e32 v178, v181, v178
	v_pk_mul_f32 v[144:145], v[144:145], v[184:185]
	v_add_f32_e32 v178, v182, v178
	v_pk_mul_f32 v[184:185], v[144:145], v[144:145]
	v_add_f32_e32 v178, v183, v178
	v_add_f32_e32 v178, v184, v178
	v_add_f32_e32 v178, v185, v178
	v_lshlrev_b32_e32 v142, 8, v188
	v_mov_b32_e32 v143, v132
	v_add_f32_dpp v178, v178, v178 quad_perm:[1,0,3,2] row_mask:0xf bank_mask:0xf bound_ctrl:1
	v_lshl_add_u64 v[142:143], s[4:5], 0, v[142:143]
	v_lshl_add_u64 v[142:143], v[142:143], 0, v[36:37]
	v_add_f32_dpp v178, v178, v178 quad_perm:[2,3,0,1] row_mask:0xf bank_mask:0xf bound_ctrl:1
	global_store_dwordx4 v[142:143], v[168:171], off nt
	v_pk_fma_f32 v[4:5], v[42:43], v[6:7], v[4:5]
	v_add_f32_dpp v178, v178, v178 row_half_mirror row_mask:0xf bank_mask:0xf bound_ctrl:1
	v_pk_fma_f32 v[160:161], v[40:41], v[6:7], v[160:161]
	v_pk_fma_f32 v[6:7], v[38:39], v[6:7], 0 op_sel_hi:[1,1,0]
	v_add_f32_dpp v178, v178, v178 row_mirror row_mask:0xf bank_mask:0xf bound_ctrl:1
	v_add_f32_e32 v178, 0x358637bd, v178
	v_rsq_f32_e32 v178, v178
	s_nop 0
	v_mul_f32_e32 v142, 0x3db504f3, v178
	v_pk_mul_f32 v[150:151], v[150:151], v[142:143] op_sel_hi:[1,0]
	v_pk_mul_f32 v[148:149], v[148:149], v[142:143] op_sel_hi:[1,0]
	v_pk_mul_f32 v[146:147], v[146:147], v[142:143] op_sel_hi:[1,0]
	v_pk_mul_f32 v[178:179], v[144:145], v[142:143] op_sel_hi:[1,0]
	v_cvt_pk_bf16_f32 v142, v150, v151
	v_cvt_pk_bf16_f32 v143, v148, v149
	v_cvt_pk_bf16_f32 v144, v146, v147
	v_cvt_pk_bf16_f32 v145, v178, v179
	ds_write_b128 v17, v[142:145] offset:816
	s_waitcnt lgkmcnt(5)
	v_pk_mul_f32 v[142:143], v[0:1], v[150:151] op_sel_hi:[0,1]
	v_cvt_pk_bf16_f32 v168, v142, v143
	v_pk_mul_f32 v[142:143], v[0:1], v[148:149] op_sel_hi:[0,1]
	v_cvt_pk_bf16_f32 v169, v142, v143
	v_pk_mul_f32 v[142:143], v[0:1], v[146:147] op_sel_hi:[0,1]
	v_cvt_pk_bf16_f32 v170, v142, v143
	v_pk_mul_f32 v[142:143], v[0:1], v[178:179] op_sel_hi:[0,1]
	v_cvt_pk_bf16_f32 v171, v142, v143
	v_pk_fma_f32 v[142:143], v[8:9], v[158:159], 0 op_sel_hi:[1,1,0]
	v_lshlrev_b32_e32 v148, 16, v112
	v_pk_fma_f32 v[142:143], v[10:11], v[166:167], v[142:143]
	v_and_b32_e32 v149, 0xffff0000, v112
	v_pk_fma_f32 v[142:143], v[12:13], v[140:141], v[142:143]
	v_lshlrev_b32_e32 v150, 8, v186
	v_pk_fma_f32 v[158:159], v[14:15], v[148:149], v[142:143]
	v_pk_fma_f32 v[142:143], v[20:21], v[156:157], 0 op_sel_hi:[1,1,0]
	v_lshlrev_b32_e32 v146, 16, v113
	v_pk_fma_f32 v[142:143], v[22:23], v[164:165], v[142:143]
	v_and_b32_e32 v147, 0xffff0000, v113
	v_pk_fma_f32 v[142:143], v[24:25], v[134:135], v[142:143]
	v_or_b32_e32 v186, 5, v19
	v_pk_fma_f32 v[156:157], v[26:27], v[146:147], v[142:143]
	v_pk_fma_f32 v[142:143], v[28:29], v[152:153], 0 op_sel_hi:[1,1,0]
	v_cmp_gt_u32_e32 vcc, s3, v186
	v_pk_fma_f32 v[142:143], v[30:31], v[162:163], v[142:143]
	v_lshlrev_b32_e32 v144, 16, v114
	v_cndmask_b32_e32 v159, 0, v159, vcc
	v_cndmask_b32_e32 v158, 0, v158, vcc
	v_and_b32_e32 v145, 0xffff0000, v114
	v_pk_fma_f32 v[142:143], v[32:33], v[46:47], v[142:143]
	v_cndmask_b32_e32 v157, 0, v157, vcc
	v_cndmask_b32_e32 v156, 0, v156, vcc
	v_mul_f32_e32 v178, 0xbfb8aa3b, v158
	v_mul_f32_e32 v179, 0xbfb8aa3b, v159
	v_pk_fma_f32 v[152:153], v[34:35], v[144:145], v[142:143]
	v_exp_f32_e32 v178, v178
	v_exp_f32_e32 v179, v179
	v_mul_f32_e32 v180, 0xbfb8aa3b, v156
	v_mul_f32_e32 v181, 0xbfb8aa3b, v157
	v_lshlrev_b32_e32 v142, 16, v115
	v_and_b32_e32 v143, 0xffff0000, v115
	v_cndmask_b32_e32 v153, 0, v153, vcc
	v_cndmask_b32_e32 v152, 0, v152, vcc
	v_exp_f32_e32 v180, v180
	v_exp_f32_e32 v181, v181
	v_pk_fma_f32 v[4:5], v[44:45], v[142:143], v[4:5]
	v_mul_f32_e32 v182, 0xbfb8aa3b, v152
	v_mul_f32_e32 v183, 0xbfb8aa3b, v153
	v_cndmask_b32_e32 v5, 0, v5, vcc
	v_cndmask_b32_e32 v4, 0, v4, vcc
	v_exp_f32_e32 v182, v182
	v_exp_f32_e32 v183, v183
	v_add_f32_e32 v178, 1.0, v178
	v_add_f32_e32 v179, 1.0, v179
	v_mul_f32_e32 v184, 0xbfb8aa3b, v4
	v_mul_f32_e32 v185, 0xbfb8aa3b, v5
	v_rcp_f32_e32 v178, v178
	v_rcp_f32_e32 v179, v179
	v_add_f32_e32 v180, 1.0, v180
	v_add_f32_e32 v181, 1.0, v181
	v_exp_f32_e32 v184, v184
	v_exp_f32_e32 v185, v185
	v_rcp_f32_e32 v180, v180
	v_rcp_f32_e32 v181, v181
	v_add_f32_e32 v182, 1.0, v182
	v_add_f32_e32 v183, 1.0, v183
	v_rcp_f32_e32 v182, v182
	v_rcp_f32_e32 v183, v183
	v_add_f32_e32 v184, 1.0, v184
	v_add_f32_e32 v185, 1.0, v185
	v_pk_mul_f32 v[158:159], v[158:159], v[178:179]
	v_rcp_f32_e32 v184, v184
	v_rcp_f32_e32 v185, v185
	v_pk_mul_f32 v[156:157], v[156:157], v[180:181]
	v_pk_mul_f32 v[178:179], v[158:159], v[158:159]
	v_pk_mul_f32 v[180:181], v[156:157], v[156:157]
	v_add_f32_e32 v178, v178, v179
	v_pk_mul_f32 v[152:153], v[152:153], v[182:183]
	v_add_f32_e32 v178, v180, v178
	v_pk_mul_f32 v[182:183], v[152:153], v[152:153]
	v_add_f32_e32 v178, v181, v178
	v_pk_mul_f32 v[4:5], v[4:5], v[184:185]
	v_add_f32_e32 v178, v182, v178
	v_pk_mul_f32 v[184:185], v[4:5], v[4:5]
	v_add_f32_e32 v178, v183, v178
	v_add_f32_e32 v178, v184, v178
	v_add_f32_e32 v178, v185, v178
	v_mov_b32_e32 v151, v132
	v_lshl_add_u64 v[150:151], s[4:5], 0, v[150:151]
	v_add_f32_dpp v178, v178, v178 quad_perm:[1,0,3,2] row_mask:0xf bank_mask:0xf bound_ctrl:1
	v_lshl_add_u64 v[150:151], v[150:151], 0, v[36:37]
	global_store_dwordx4 v[150:151], v[168:171], off nt
	v_add_f32_dpp v178, v178, v178 quad_perm:[2,3,0,1] row_mask:0xf bank_mask:0xf bound_ctrl:1
	v_pk_fma_f32 v[164:165], v[20:21], v[164:165], 0 op_sel_hi:[1,1,0]
	v_or_b32_e32 v184, 6, v19
	v_add_f32_dpp v178, v178, v178 row_half_mirror row_mask:0xf bank_mask:0xf bound_ctrl:1
	v_pk_fma_f32 v[164:165], v[22:23], v[134:135], v[164:165]
	v_pk_fma_f32 v[162:163], v[28:29], v[162:163], 0 op_sel_hi:[1,1,0]
	v_add_f32_dpp v178, v178, v178 row_mirror row_mask:0xf bank_mask:0xf bound_ctrl:1
	v_add_f32_e32 v178, 0x358637bd, v178
	v_rsq_f32_e32 v178, v178
	v_pk_fma_f32 v[164:165], v[24:25], v[146:147], v[164:165]
	v_cmp_gt_u32_e32 vcc, s3, v184
	v_pk_fma_f32 v[162:163], v[30:31], v[46:47], v[162:163]
	v_mul_f32_e32 v150, 0x3db504f3, v178
	v_pk_mul_f32 v[158:159], v[158:159], v[150:151] op_sel_hi:[1,0]
	v_pk_mul_f32 v[156:157], v[156:157], v[150:151] op_sel_hi:[1,0]
	v_pk_mul_f32 v[168:169], v[152:153], v[150:151] op_sel_hi:[1,0]
	v_pk_mul_f32 v[4:5], v[4:5], v[150:151] op_sel_hi:[1,0]
	v_cvt_pk_bf16_f32 v150, v158, v159
	v_cvt_pk_bf16_f32 v151, v156, v157
	v_cvt_pk_bf16_f32 v152, v168, v169
	v_cvt_pk_bf16_f32 v153, v4, v5
	ds_write_b128 v17, v[150:153] offset:1088
	v_pk_mul_f32 v[152:153], v[0:1], v[156:157] op_sel:[1,0]
	v_pk_fma_f32 v[156:157], v[8:9], v[166:167], 0 op_sel_hi:[1,1,0]
	v_pk_mul_f32 v[150:151], v[0:1], v[158:159] op_sel:[1,0]
	v_pk_fma_f32 v[156:157], v[10:11], v[140:141], v[156:157]
	v_cvt_pk_bf16_f32 v150, v150, v151
	v_cvt_pk_bf16_f32 v151, v152, v153
	v_pk_mul_f32 v[152:153], v[0:1], v[168:169] op_sel:[1,0]
	v_pk_mul_f32 v[0:1], v[0:1], v[4:5] op_sel:[1,0]
	v_lshlrev_b32_e32 v4, 16, v116
	v_and_b32_e32 v5, 0xffff0000, v116
	v_pk_fma_f32 v[156:157], v[12:13], v[148:149], v[156:157]
	v_lshlrev_b32_e32 v158, 16, v117
	v_pk_fma_f32 v[156:157], v[14:15], v[4:5], v[156:157]
	v_and_b32_e32 v159, 0xffff0000, v117
	v_pk_fma_f32 v[164:165], v[26:27], v[158:159], v[164:165]
	v_cndmask_b32_e32 v157, 0, v157, vcc
	v_cndmask_b32_e32 v156, 0, v156, vcc
	v_lshlrev_b32_e32 v166, 16, v118
	v_and_b32_e32 v167, 0xffff0000, v118
	v_pk_fma_f32 v[162:163], v[32:33], v[144:145], v[162:163]
	v_cndmask_b32_e32 v165, 0, v165, vcc
	v_cndmask_b32_e32 v164, 0, v164, vcc
	v_mul_f32_e32 v170, 0xbfb8aa3b, v156
	v_mul_f32_e32 v171, 0xbfb8aa3b, v157
	v_pk_fma_f32 v[162:163], v[34:35], v[166:167], v[162:163]
	v_exp_f32_e32 v170, v170
	v_exp_f32_e32 v171, v171
	v_mul_f32_e32 v178, 0xbfb8aa3b, v164
	v_mul_f32_e32 v179, 0xbfb8aa3b, v165
	v_lshlrev_b32_e32 v168, 16, v119
	v_and_b32_e32 v169, 0xffff0000, v119
	v_pk_fma_f32 v[160:161], v[42:43], v[142:143], v[160:161]
	v_cndmask_b32_e32 v163, 0, v163, vcc
	v_cndmask_b32_e32 v162, 0, v162, vcc
	v_exp_f32_e32 v178, v178
	v_exp_f32_e32 v179, v179
	v_pk_fma_f32 v[160:161], v[44:45], v[168:169], v[160:161]
	v_mul_f32_e32 v180, 0xbfb8aa3b, v162
	v_mul_f32_e32 v181, 0xbfb8aa3b, v163
	v_cndmask_b32_e32 v161, 0, v161, vcc
	v_cndmask_b32_e32 v160, 0, v160, vcc
	v_exp_f32_e32 v180, v180
	v_exp_f32_e32 v181, v181
	v_add_f32_e32 v170, 1.0, v170
	v_add_f32_e32 v171, 1.0, v171
	v_mul_f32_e32 v182, 0xbfb8aa3b, v160
	v_mul_f32_e32 v183, 0xbfb8aa3b, v161
	v_rcp_f32_e32 v170, v170
	v_rcp_f32_e32 v171, v171
	v_add_f32_e32 v178, 1.0, v178
	v_add_f32_e32 v179, 1.0, v179
	v_exp_f32_e32 v182, v182
	v_exp_f32_e32 v183, v183
	v_rcp_f32_e32 v178, v178
	v_rcp_f32_e32 v179, v179
	v_add_f32_e32 v180, 1.0, v180
	v_add_f32_e32 v181, 1.0, v181
	v_rcp_f32_e32 v180, v180
	v_rcp_f32_e32 v181, v181
	v_add_f32_e32 v182, 1.0, v182
	v_add_f32_e32 v183, 1.0, v183
	v_pk_mul_f32 v[156:157], v[156:157], v[170:171]
	v_rcp_f32_e32 v182, v182
	v_rcp_f32_e32 v183, v183
	v_pk_mul_f32 v[164:165], v[164:165], v[178:179]
	v_pk_mul_f32 v[170:171], v[156:157], v[156:157]
	v_pk_mul_f32 v[178:179], v[164:165], v[164:165]
	v_add_f32_e32 v170, v170, v171
	v_pk_mul_f32 v[162:163], v[162:163], v[180:181]
	v_add_f32_e32 v170, v178, v170
	v_pk_mul_f32 v[180:181], v[162:163], v[162:163]
	v_add_f32_e32 v170, v179, v170
	v_pk_mul_f32 v[160:161], v[160:161], v[182:183]
	v_add_f32_e32 v170, v180, v170
	v_pk_mul_f32 v[182:183], v[160:161], v[160:161]
	v_add_f32_e32 v170, v181, v170
	v_add_f32_e32 v170, v182, v170
	v_add_f32_e32 v170, v183, v170
	v_cvt_pk_bf16_f32 v152, v152, v153
	v_cvt_pk_bf16_f32 v153, v0, v1
	v_add_f32_dpp v170, v170, v170 quad_perm:[1,0,3,2] row_mask:0xf bank_mask:0xf bound_ctrl:1
	v_lshlrev_b32_e32 v0, 8, v186
	v_mov_b32_e32 v1, v132
	v_add_f32_dpp v170, v170, v170 quad_perm:[2,3,0,1] row_mask:0xf bank_mask:0xf bound_ctrl:1
	v_lshl_add_u64 v[0:1], s[4:5], 0, v[0:1]
	v_lshl_add_u64 v[0:1], v[0:1], 0, v[36:37]
	v_add_f32_dpp v170, v170, v170 row_half_mirror row_mask:0xf bank_mask:0xf bound_ctrl:1
	global_store_dwordx4 v[0:1], v[150:153], off nt
	v_pk_fma_f32 v[8:9], v[8:9], v[140:141], 0 op_sel_hi:[1,1,0]
	v_add_f32_dpp v170, v170, v170 row_mirror row_mask:0xf bank_mask:0xf bound_ctrl:1
	v_add_f32_e32 v170, 0x358637bd, v170
	v_rsq_f32_e32 v170, v170
	v_pk_fma_f32 v[8:9], v[10:11], v[148:149], v[8:9]
	v_pk_fma_f32 v[10:11], v[20:21], v[134:135], 0 op_sel_hi:[1,1,0]
	v_pk_fma_f32 v[4:5], v[12:13], v[4:5], v[8:9]
	v_mul_f32_e32 v0, 0x3db504f3, v170
	v_pk_mul_f32 v[156:157], v[156:157], v[0:1] op_sel_hi:[1,0]
	v_pk_mul_f32 v[164:165], v[164:165], v[0:1] op_sel_hi:[1,0]
	v_pk_mul_f32 v[162:163], v[162:163], v[0:1] op_sel_hi:[1,0]
	v_pk_mul_f32 v[0:1], v[160:161], v[0:1] op_sel_hi:[1,0]
	v_cvt_pk_bf16_f32 v150, v156, v157
	v_cvt_pk_bf16_f32 v151, v164, v165
	v_cvt_pk_bf16_f32 v152, v162, v163
	v_cvt_pk_bf16_f32 v153, v0, v1
	ds_write_b128 v17, v[150:153] offset:1360
	v_pk_mul_f32 v[150:151], v[2:3], v[156:157] op_sel_hi:[0,1]
	v_lshlrev_b32_e32 v156, 16, v120
	v_and_b32_e32 v157, 0xffff0000, v120
	v_pk_fma_f32 v[10:11], v[22:23], v[146:147], v[10:11]
	v_pk_fma_f32 v[12:13], v[28:29], v[46:47], 0 op_sel_hi:[1,1,0]
	v_or_b32_e32 v19, 7, v19
	v_pk_fma_f32 v[4:5], v[14:15], v[156:157], v[4:5]
	v_lshlrev_b32_e32 v8, 16, v121
	v_and_b32_e32 v9, 0xffff0000, v121
	v_pk_fma_f32 v[10:11], v[24:25], v[158:159], v[10:11]
	v_pk_fma_f32 v[12:13], v[30:31], v[144:145], v[12:13]
	v_cmp_gt_u32_e32 vcc, s3, v19
	v_pk_mul_f32 v[152:153], v[2:3], v[164:165] op_sel_hi:[0,1]
	v_pk_fma_f32 v[8:9], v[26:27], v[8:9], v[10:11]
	v_lshlrev_b32_e32 v10, 16, v122
	v_and_b32_e32 v11, 0xffff0000, v122
	v_pk_fma_f32 v[12:13], v[32:33], v[166:167], v[12:13]
	v_pk_fma_f32 v[6:7], v[40:41], v[142:143], v[6:7]
	v_cndmask_b32_e32 v4, 0, v4, vcc
	v_cvt_pk_bf16_f32 v150, v150, v151
	v_cvt_pk_bf16_f32 v151, v152, v153
	v_pk_mul_f32 v[152:153], v[2:3], v[162:163] op_sel_hi:[0,1]
	v_pk_mul_f32 v[0:1], v[2:3], v[0:1] op_sel_hi:[0,1]
	v_pk_fma_f32 v[10:11], v[34:35], v[10:11], v[12:13]
	v_lshlrev_b32_e32 v12, 16, v123
	v_and_b32_e32 v13, 0xffff0000, v123
	v_pk_fma_f32 v[6:7], v[42:43], v[168:169], v[6:7]
	v_cndmask_b32_e32 v5, 0, v5, vcc
	v_mul_f32_e32 v2, 0xbfb8aa3b, v4
	v_pk_fma_f32 v[6:7], v[44:45], v[12:13], v[6:7]
	v_exp_f32_e32 v2, v2
	v_mul_f32_e32 v12, 0xbfb8aa3b, v5
	v_exp_f32_e32 v13, v12
	v_cndmask_b32_e32 v9, 0, v9, vcc
	v_add_f32_e32 v2, 1.0, v2
	v_cndmask_b32_e32 v8, 0, v8, vcc
	v_rcp_f32_e32 v12, v2
	v_add_f32_e32 v2, 1.0, v13
	v_cndmask_b32_e32 v10, 0, v10, vcc
	v_rcp_f32_e32 v13, v2
	v_mul_f32_e32 v2, 0xbfb8aa3b, v8
	v_mul_f32_e32 v14, 0xbfb8aa3b, v9
	v_exp_f32_e32 v2, v2
	v_exp_f32_e32 v15, v14
	v_mul_f32_e32 v14, 0xbfb8aa3b, v10
	v_exp_f32_e32 v20, v14
	v_cndmask_b32_e32 v6, 0, v6, vcc
	v_add_f32_e32 v2, 1.0, v2
	v_cndmask_b32_e32 v7, 0, v7, vcc
	v_cndmask_b32_e32 v11, 0, v11, vcc
	v_rcp_f32_e32 v14, v2
	v_add_f32_e32 v2, 1.0, v15
	v_add_f32_e32 v15, 1.0, v20
	v_mul_f32_e32 v21, 0xbfb8aa3b, v6
	v_rcp_f32_e32 v20, v15
	v_mul_f32_e32 v15, 0xbfb8aa3b, v11
	v_exp_f32_e32 v21, v21
	v_mul_f32_e32 v22, 0xbfb8aa3b, v7
	v_exp_f32_e32 v23, v22
	v_exp_f32_e32 v15, v15
	v_add_f32_e32 v21, 1.0, v21
	v_rcp_f32_e32 v22, v21
	v_add_f32_e32 v21, 1.0, v23
	v_add_f32_e32 v15, 1.0, v15
	v_rcp_f32_e32 v23, v21
	v_rcp_f32_e32 v21, v15
	v_rcp_f32_e32 v15, v2
	v_pk_mul_f32 v[4:5], v[4:5], v[12:13]
	v_pk_mul_f32 v[6:7], v[6:7], v[22:23]
	v_pk_mul_f32 v[12:13], v[4:5], v[4:5]
	v_pk_mul_f32 v[8:9], v[8:9], v[14:15]
	v_add_f32_e32 v2, v12, v13
	v_pk_mul_f32 v[14:15], v[8:9], v[8:9]
	v_pk_mul_f32 v[10:11], v[10:11], v[20:21]
	v_add_f32_e32 v2, v14, v2
	v_pk_mul_f32 v[20:21], v[10:11], v[10:11]
	v_add_f32_e32 v2, v15, v2
	v_add_f32_e32 v2, v20, v2
	v_pk_mul_f32 v[22:23], v[6:7], v[6:7]
	v_add_f32_e32 v2, v21, v2
	v_add_f32_e32 v2, v22, v2
	v_add_f32_e32 v2, v23, v2
	v_cvt_pk_bf16_f32 v152, v152, v153
	v_cvt_pk_bf16_f32 v153, v0, v1
	v_add_f32_dpp v2, v2, v2 quad_perm:[1,0,3,2] row_mask:0xf bank_mask:0xf bound_ctrl:1
	v_lshlrev_b32_e32 v0, 8, v184
	v_mov_b32_e32 v1, v132
	v_add_f32_dpp v2, v2, v2 quad_perm:[2,3,0,1] row_mask:0xf bank_mask:0xf bound_ctrl:1
	v_lshl_add_u64 v[0:1], s[4:5], 0, v[0:1]
	v_lshl_add_u64 v[0:1], v[0:1], 0, v[36:37]
	v_add_f32_dpp v2, v2, v2 row_half_mirror row_mask:0xf bank_mask:0xf bound_ctrl:1
	global_store_dwordx4 v[0:1], v[150:153], off nt
	s_nop 0
	v_add_f32_dpp v2, v2, v2 row_mirror row_mask:0xf bank_mask:0xf bound_ctrl:1
	v_add_f32_e32 v2, 0x358637bd, v2
	v_rsq_f32_e32 v2, v2
	s_nop 0
	v_mul_f32_e32 v0, 0x3db504f3, v2
	v_pk_mul_f32 v[12:13], v[4:5], v[0:1] op_sel_hi:[1,0]
	v_pk_mul_f32 v[8:9], v[8:9], v[0:1] op_sel_hi:[1,0]
	v_pk_mul_f32 v[10:11], v[10:11], v[0:1] op_sel_hi:[1,0]
	v_pk_mul_f32 v[14:15], v[6:7], v[0:1] op_sel_hi:[1,0]
	v_cvt_pk_bf16_f32 v4, v12, v13
	v_cvt_pk_bf16_f32 v5, v8, v9
	v_cvt_pk_bf16_f32 v6, v10, v11
	v_cvt_pk_bf16_f32 v7, v14, v15
	ds_write_b128 v17, v[4:7] offset:1632
	v_mov_b32_e32 v4, v3
	v_pk_mul_f32 v[0:1], v[4:5], v[12:13] op_sel_hi:[0,1]
	v_pk_mul_f32 v[2:3], v[4:5], v[8:9] op_sel_hi:[0,1]
	v_cvt_pk_bf16_f32 v0, v0, v1
	v_cvt_pk_bf16_f32 v1, v2, v3
	v_pk_mul_f32 v[2:3], v[4:5], v[10:11] op_sel_hi:[0,1]
	v_pk_mul_f32 v[4:5], v[4:5], v[14:15] op_sel_hi:[0,1]
	v_cvt_pk_bf16_f32 v2, v2, v3
	v_cvt_pk_bf16_f32 v3, v4, v5
	v_lshlrev_b32_e32 v4, 8, v19
	v_mov_b32_e32 v5, v132
	v_lshl_add_u64 v[4:5], s[4:5], 0, v[4:5]
	v_lshl_add_u64 v[4:5], v[4:5], 0, v[36:37]
	global_store_dwordx4 v[4:5], v[0:3], off nt
